# v46 + causal attention (forgetting + differential units): a wave branches over the QK^T and PV matrix segments of key tiles wholly above its 32 query rows (their scores are all masked to -inf anyway;
# baseline (speedup 1.0000x reference)
.LBB0_645:
	v_add_u32_e32 v218, s11, v192
	v_add_u32_e32 v81, 1, v218
	v_mad_i64_i32 v[82:83], s[0:1], v81, s33, v[164:165]
	v_add_u32_e32 v86, 33, v218
	v_mad_i64_i32 v[84:85], s[0:1], v86, s33, v[164:165]
	global_load_dwordx4 v[146:149], v[82:83], off
	global_load_dwordx4 v[150:153], v[84:85], off
	v_mad_i64_i32 v[82:83], s[0:1], v81, s33, v[166:167]
	v_mad_i64_i32 v[84:85], s[0:1], v86, s33, v[166:167]
	global_load_dwordx4 v[154:157], v[82:83], off
	global_load_dwordx4 v[158:161], v[84:85], off
	s_waitcnt lgkmcnt(0)
	s_sub_i32 s0, s11, s27
	s_cmp_ge_i32 s0, 95
	s_cbranch_scc1 .Lmskip_fox_0
	ds_read_b128 v[228:231], v191 offset:49152
	ds_read_b128 v[232:235], v190 offset:49152
	ds_read_b128 v[236:239], v191 offset:57344
	ds_read_b128 v[248:251], v190 offset:57344
	ds_read_b128 v[252:255], v189 offset:49152
	s_waitcnt lgkmcnt(4)
	v_mfma_f32_32x32x16_bf16 v[98:113], v[228:231], v[142:145], 0
	ds_read_b128 v[228:231], v189 offset:57344
	s_waitcnt lgkmcnt(4)
	v_mfma_f32_32x32x16_bf16 v[98:113], v[232:235], v[138:141], v[98:113]
	ds_read_b128 v[232:235], v188 offset:49152
	s_waitcnt lgkmcnt(4)
	v_mfma_f32_32x32x16_bf16 v[82:97], v[236:239], v[142:145], 0
	ds_read_b128 v[236:239], v188 offset:57344
	s_waitcnt lgkmcnt(4)
	v_mfma_f32_32x32x16_bf16 v[82:97], v[248:251], v[138:141], v[82:97]
	ds_read_b128 v[248:251], v191 offset:49280
	s_waitcnt lgkmcnt(4)
	v_mfma_f32_32x32x16_bf16 v[98:113], v[252:255], v[134:137], v[98:113]
	ds_read_b128 v[252:255], v191 offset:57472
	s_waitcnt lgkmcnt(4)
	v_mfma_f32_32x32x16_bf16 v[82:97], v[228:231], v[134:137], v[82:97]
	ds_read_b128 v[228:231], v190 offset:49280
	s_waitcnt lgkmcnt(4)
	v_mfma_f32_32x32x16_bf16 v[98:113], v[232:235], v[130:133], v[98:113]
	ds_read_b128 v[232:235], v190 offset:57472
	s_waitcnt lgkmcnt(4)
	v_mfma_f32_32x32x16_bf16 v[82:97], v[236:239], v[130:133], v[82:97]
	ds_read_b128 v[236:239], v189 offset:49280
	s_waitcnt lgkmcnt(4)
	v_mfma_f32_32x32x16_bf16 v[98:113], v[248:251], v[126:129], v[98:113]
	ds_read_b128 v[248:251], v189 offset:57472
	s_waitcnt lgkmcnt(4)
	v_mfma_f32_32x32x16_bf16 v[82:97], v[252:255], v[126:129], v[82:97]
	ds_read_b128 v[252:255], v188 offset:49280
	s_waitcnt lgkmcnt(4)
	v_mfma_f32_32x32x16_bf16 v[98:113], v[228:231], v[122:125], v[98:113]
	ds_read_b128 v[228:231], v188 offset:57472
	s_waitcnt lgkmcnt(4)
	v_mfma_f32_32x32x16_bf16 v[82:97], v[232:235], v[122:125], v[82:97]
	s_waitcnt lgkmcnt(3)
	v_mfma_f32_32x32x16_bf16 v[98:113], v[236:239], v[118:121], v[98:113]
	s_waitcnt lgkmcnt(2)
	v_mfma_f32_32x32x16_bf16 v[82:97], v[248:251], v[118:121], v[82:97]
	s_waitcnt lgkmcnt(1)
	v_mfma_f32_32x32x16_bf16 v[98:113], v[252:255], v[114:117], v[98:113]
	s_waitcnt lgkmcnt(0)
	v_mfma_f32_32x32x16_bf16 v[82:97], v[228:231], v[114:117], v[82:97]
.Lmskip_fox_0:
	v_exp_f32_e32 v226, v66
	v_add_f32_e32 v66, 0, v215
	v_add_f32_e32 v66, v217, v66
	v_add_f32_e32 v66, v213, v66
	v_add_f32_e32 v66, v216, v66
	v_add_f32_e32 v66, v211, v66
	v_add_f32_e32 v66, v214, v66
	v_add_f32_e32 v66, v210, v66
	v_add_f32_e32 v66, v212, v66
	v_add_f32_e32 v66, v207, v66
	v_add_f32_e32 v66, v209, v66
	v_add_f32_e32 v66, v205, v66
	v_add_f32_e32 v66, v208, v66
	v_exp_f32_e32 v80, v80
	v_add_f32_e32 v66, v203, v66
	v_exp_f32_e32 v1, v1
	v_add_f32_e32 v66, v206, v66
	v_exp_f32_e32 v78, v78
	v_add_f32_e32 v66, v202, v66
	v_exp_f32_e32 v79, v79
	v_add_f32_e32 v66, v204, v66
	v_exp_f32_e32 v76, v76
	v_add_f32_e32 v66, v80, v66
	v_exp_f32_e32 v77, v77
	v_add_f32_e32 v66, v1, v66
	v_exp_f32_e32 v81, v74
	v_add_f32_e32 v66, v78, v66
	v_exp_f32_e32 v219, v75
	v_add_f32_e32 v66, v79, v66
	v_exp_f32_e32 v220, v72
	v_add_f32_e32 v66, v76, v66
	v_exp_f32_e32 v221, v73
	v_add_f32_e32 v66, v77, v66
	v_exp_f32_e32 v222, v70
	v_add_f32_e32 v66, v81, v66
	v_exp_f32_e32 v223, v71
	v_add_f32_e32 v66, v219, v66
	v_exp_f32_e32 v224, v68
	v_add_f32_e32 v66, v220, v66
	v_exp_f32_e32 v225, v69
	v_add_f32_e32 v66, v221, v66
	v_add_f32_e32 v66, v222, v66
	v_exp_f32_e32 v227, v67
	v_add_f32_e32 v66, v223, v66
	v_add_f32_e32 v66, v224, v66
	v_add_f32_e32 v66, v225, v66
	v_add_f32_e32 v66, v226, v66
	v_add_f32_e32 v200, v227, v66
	v_mov_b32_e32 v201, v200
	v_cvt_pk_bf16_f32 v66, v215, v217
	v_cvt_pk_bf16_f32 v67, v213, v216
	v_cvt_pk_bf16_f32 v68, v211, v214
	v_cvt_pk_bf16_f32 v69, v210, v212
	v_cvt_pk_bf16_f32 v70, v207, v209
	v_cvt_pk_bf16_f32 v71, v205, v208
	v_cvt_pk_bf16_f32 v72, v203, v206
	v_cvt_pk_bf16_f32 v73, v202, v204
	v_cvt_pk_bf16_f32 v74, v80, v1
	v_cvt_pk_bf16_f32 v75, v78, v79
	v_cvt_pk_bf16_f32 v76, v76, v77
	v_cvt_pk_bf16_f32 v77, v81, v219
	v_cvt_pk_bf16_f32 v78, v220, v221
	v_cvt_pk_bf16_f32 v79, v222, v223
	v_cvt_pk_bf16_f32 v80, v224, v225
	v_cvt_pk_bf16_f32 v81, v226, v227
	s_nop 1
	v_permlane32_swap_b32_e32 v200, v201
	v_permlane32_swap_b32_e32 v66, v68
	v_permlane32_swap_b32_e32 v67, v69
	v_permlane32_swap_b32_e32 v70, v72
	v_permlane32_swap_b32_e32 v71, v73
	v_permlane32_swap_b32_e32 v74, v76
	v_permlane32_swap_b32_e32 v75, v77
	v_permlane32_swap_b32_e32 v78, v80
	v_permlane32_swap_b32_e32 v79, v81
	s_waitcnt lgkmcnt(0)
	s_sub_i32 s0, s11, s27
	s_cmp_ge_i32 s0, 159
	s_cbranch_scc1 .Lmskip_fox_1
	ds_read_b64_tr_b16 v[202:203], v183 offset:0
	ds_read_b64_tr_b16 v[204:205], v183 offset:0x800
	ds_read_b64_tr_b16 v[206:207], v183 offset:0x1000
	ds_read_b64_tr_b16 v[208:209], v183 offset:0x1800
	ds_read_b64_tr_b16 v[210:211], v183 offset:0x2000
	ds_read_b64_tr_b16 v[212:213], v183 offset:0x2800
	ds_read_b64_tr_b16 v[214:215], v183 offset:0x3000
	ds_read_b64_tr_b16 v[216:217], v183 offset:0x3800
	s_nop 0
	s_waitcnt lgkmcnt(6)
	v_mfma_f32_32x32x16_bf16 v[50:65], v[66:69], v[202:205], v[50:65]
	ds_read_b64_tr_b16 v[202:203], v183 offset:0x200
	ds_read_b64_tr_b16 v[204:205], v183 offset:0xa00
	s_waitcnt lgkmcnt(6)
	v_mfma_f32_32x32x16_bf16 v[50:65], v[70:73], v[206:209], v[50:65]
	ds_read_b64_tr_b16 v[206:207], v183 offset:0x1200
	ds_read_b64_tr_b16 v[208:209], v183 offset:0x1a00
	s_waitcnt lgkmcnt(6)
	v_mfma_f32_32x32x16_bf16 v[50:65], v[74:77], v[210:213], v[50:65]
	ds_read_b64_tr_b16 v[210:211], v183 offset:0x2200
	ds_read_b64_tr_b16 v[212:213], v183 offset:0x2a00
	s_waitcnt lgkmcnt(6)
	v_mfma_f32_32x32x16_bf16 v[50:65], v[78:81], v[214:217], v[50:65]
	ds_read_b64_tr_b16 v[214:215], v183 offset:0x3200
	ds_read_b64_tr_b16 v[216:217], v183 offset:0x3a00
	s_waitcnt lgkmcnt(6)
	v_mfma_f32_32x32x16_bf16 v[34:49], v[66:69], v[202:205], v[34:49]
	ds_read_b64_tr_b16 v[202:203], v183 offset:0x400
	ds_read_b64_tr_b16 v[204:205], v183 offset:0xc00
	s_waitcnt lgkmcnt(6)
	v_mfma_f32_32x32x16_bf16 v[34:49], v[70:73], v[206:209], v[34:49]
	ds_read_b64_tr_b16 v[206:207], v183 offset:0x1400
	ds_read_b64_tr_b16 v[208:209], v183 offset:0x1c00
	s_waitcnt lgkmcnt(6)
	v_mfma_f32_32x32x16_bf16 v[34:49], v[74:77], v[210:213], v[34:49]
	ds_read_b64_tr_b16 v[210:211], v183 offset:0x2400
	ds_read_b64_tr_b16 v[212:213], v183 offset:0x2c00
	s_waitcnt lgkmcnt(6)
	v_mfma_f32_32x32x16_bf16 v[34:49], v[78:81], v[214:217], v[34:49]
	ds_read_b64_tr_b16 v[214:215], v183 offset:0x3400
	ds_read_b64_tr_b16 v[216:217], v183 offset:0x3c00
	s_waitcnt lgkmcnt(6)
	v_mfma_f32_32x32x16_bf16 v[18:33], v[66:69], v[202:205], v[18:33]
	ds_read_b64_tr_b16 v[202:203], v183 offset:0x600
	ds_read_b64_tr_b16 v[204:205], v183 offset:0xe00
	s_waitcnt lgkmcnt(6)
	v_mfma_f32_32x32x16_bf16 v[18:33], v[70:73], v[206:209], v[18:33]
	ds_read_b64_tr_b16 v[206:207], v183 offset:0x1600
	ds_read_b64_tr_b16 v[208:209], v183 offset:0x1e00
	s_waitcnt lgkmcnt(6)
	v_mfma_f32_32x32x16_bf16 v[18:33], v[74:77], v[210:213], v[18:33]
	ds_read_b64_tr_b16 v[210:211], v183 offset:0x2600
	ds_read_b64_tr_b16 v[212:213], v183 offset:0x2e00
	s_waitcnt lgkmcnt(6)
	v_mfma_f32_32x32x16_bf16 v[18:33], v[78:81], v[214:217], v[18:33]
	ds_read_b64_tr_b16 v[214:215], v183 offset:0x3600
	ds_read_b64_tr_b16 v[216:217], v183 offset:0x3e00
	s_waitcnt lgkmcnt(6)
	v_mfma_f32_32x32x16_bf16 v[2:17], v[66:69], v[202:205], v[2:17]
	s_waitcnt lgkmcnt(4)
	v_mfma_f32_32x32x16_bf16 v[2:17], v[70:73], v[206:209], v[2:17]
	s_waitcnt lgkmcnt(2)
	v_mfma_f32_32x32x16_bf16 v[2:17], v[74:77], v[210:213], v[2:17]
	s_waitcnt lgkmcnt(0)
	v_mfma_f32_32x32x16_bf16 v[2:17], v[78:81], v[214:217], v[2:17]
.Lmskip_fox_1:
	ds_read_b128 v[66:69], v198
	ds_read_b128 v[70:73], v198 offset:32
	ds_read_b128 v[202:205], v198 offset:128
	ds_read_b128 v[206:209], v198 offset:160
	ds_read_b128 v[76:79], v198 offset:64
	ds_read_b128 v[210:213], v198 offset:96
	ds_read_b128 v[214:217], v198 offset:192
	ds_read_b128 v[220:223], v198 offset:224
	s_waitcnt lgkmcnt(7)
	v_xor_b32_e32 v69, 0x80000000, v69
	s_waitcnt lgkmcnt(3)
	v_xor_b32_e32 v225, 0x80000000, v79
	v_xor_b32_e32 v224, 0x80000000, v78
	v_xor_b32_e32 v68, 0x80000000, v68
	v_xor_b32_e32 v73, 0x80000000, v73
	v_xor_b32_e32 v72, 0x80000000, v72
	s_waitcnt lgkmcnt(2)
	v_xor_b32_e32 v81, 0x80000000, v213
	v_xor_b32_e32 v80, 0x80000000, v212
	v_fma_f32 v74, v110, s12, -v210
	v_fma_f32 v75, v111, s12, -v211
	v_fma_f32 v78, v106, s12, -v76
	v_fma_f32 v79, v107, s12, -v77
	v_fma_f32 v102, v102, s12, -v70
	v_fma_f32 v103, v103, s12, -v71
	v_fma_f32 v106, v108, s12, v224
	v_fma_f32 v107, v109, s12, v225
	v_xor_b32_e32 v109, 0x80000000, v205
	v_xor_b32_e32 v108, 0x80000000, v204
	v_xor_b32_e32 v111, 0x80000000, v209
	v_xor_b32_e32 v110, 0x80000000, v208
	s_waitcnt lgkmcnt(1)
	v_xor_b32_e32 v77, 0x80000000, v217
	v_xor_b32_e32 v76, 0x80000000, v216
	s_waitcnt lgkmcnt(0)
	v_xor_b32_e32 v71, 0x80000000, v223
	v_xor_b32_e32 v70, 0x80000000, v222
	v_fma_f32 v80, v112, s12, v80
	v_fma_f32 v81, v113, s12, v81
	v_fma_f32 v104, v104, s12, v72
	v_fma_f32 v105, v105, s12, v73
	v_fma_f32 v100, v100, s12, v68
	v_fma_f32 v101, v101, s12, v69
	v_fma_f32 v98, v98, s12, -v66
	v_fma_f32 v99, v99, s12, -v67
	v_fma_f32 v66, v94, s12, -v220
	v_fma_f32 v67, v95, s12, -v221
	v_fma_f32 v68, v90, s12, -v214
	v_fma_f32 v69, v91, s12, -v215
	v_fma_f32 v72, v86, s12, -v206
	v_fma_f32 v73, v87, s12, -v207
	v_fma_f32 v70, v96, s12, v70
	v_fma_f32 v71, v97, s12, v71
	v_fma_f32 v76, v92, s12, v76
	v_fma_f32 v77, v93, s12, v77
	v_fma_f32 v86, v88, s12, v110
	v_fma_f32 v87, v89, s12, v111
	v_fma_f32 v84, v84, s12, v108
	v_fma_f32 v85, v85, s12, v109
	s_cmp_le_i32 s11, s27
	v_fma_f32 v82, v82, s12, -v202
	v_fma_f32 v83, v83, s12, -v203
	s_cbranch_scc1 .LBB0_647
	v_add_u32_e32 v1, 64, v199
	v_cmp_gt_i32_e64 s[92:93], 26, v1
	v_cmp_gt_i32_e64 s[94:95], 27, v1
	v_cmp_gt_i32_e64 s[90:91], 25, v1
	s_and_b64 s[92:93], s[94:95], s[92:93]
	v_cmp_gt_i32_e64 s[88:89], 24, v1
	s_and_b64 s[90:91], s[92:93], s[90:91]
	v_cmp_gt_i32_e64 s[86:87], 19, v1
	s_and_b64 s[88:89], s[90:91], s[88:89]
	v_cmp_gt_i32_e64 s[84:85], 18, v1
	s_and_b64 s[86:87], s[88:89], s[86:87]
	v_cmp_gt_i32_e64 s[82:83], 17, v1
	s_and_b64 s[84:85], s[86:87], s[84:85]
	v_cmp_gt_i32_e64 s[80:81], 16, v1
	s_and_b64 s[82:83], s[84:85], s[82:83]
	v_cmp_gt_i32_e64 s[78:79], 11, v1
	s_and_b64 s[80:81], s[82:83], s[80:81]
	v_cmp_gt_i32_e64 s[76:77], 10, v1
	s_and_b64 s[78:79], s[80:81], s[78:79]
	v_cmp_gt_i32_e64 s[74:75], 9, v1
	s_and_b64 s[76:77], s[78:79], s[76:77]
	v_cmp_gt_i32_e64 s[72:73], 8, v1
	s_and_b64 s[74:75], s[76:77], s[74:75]
	v_cmp_gt_i32_e64 s[70:71], 3, v1
	s_and_b64 s[72:73], s[74:75], s[72:73]
	v_cmp_gt_i32_e64 s[68:69], 2, v1
	s_and_b64 s[70:71], s[72:73], s[70:71]
	v_cmp_gt_i32_e64 s[2:3], 1, v1
	s_and_b64 s[68:69], s[70:71], s[68:69]
	v_cmp_gt_i32_e64 s[0:1], 0, v1
	s_and_b64 s[2:3], s[68:69], s[2:3]
	s_and_b64 s[0:1], s[2:3], s[0:1]
	v_cmp_gt_i32_e64 s[66:67], 58, v1
	v_cndmask_b32_e64 v98, v98, v175, s[0:1]
	v_cmp_gt_i32_e64 s[0:1], 59, v1
	v_cmp_gt_i32_e64 s[64:65], 57, v1
	v_cmp_gt_i32_e64 s[62:63], 56, v1
	v_cndmask_b32_e64 v71, v71, v175, s[0:1]
	s_and_b64 s[0:1], s[0:1], s[66:67]
	v_cndmask_b32_e64 v70, v70, v175, s[0:1]
	s_and_b64 s[0:1], s[0:1], s[64:65]
	v_cmp_gt_i32_e64 s[60:61], 51, v1
	v_cndmask_b32_e64 v67, v67, v175, s[0:1]
	s_and_b64 s[0:1], s[0:1], s[62:63]
	v_cmp_gt_i32_e64 s[58:59], 50, v1
	v_cndmask_b32_e64 v66, v66, v175, s[0:1]
	s_and_b64 s[0:1], s[0:1], s[60:61]
	v_cmp_gt_i32_e64 s[56:57], 49, v1
	v_cndmask_b32_e64 v77, v77, v175, s[0:1]
	s_and_b64 s[0:1], s[0:1], s[58:59]
	v_cmp_gt_i32_e64 s[54:55], 48, v1
	v_cndmask_b32_e64 v76, v76, v175, s[0:1]
	s_and_b64 s[0:1], s[0:1], s[56:57]
	v_cmp_gt_i32_e64 s[52:53], 43, v1
	v_cndmask_b32_e64 v69, v69, v175, s[0:1]
	s_and_b64 s[0:1], s[0:1], s[54:55]
	v_cmp_gt_i32_e64 s[50:51], 42, v1
	v_cndmask_b32_e64 v68, v68, v175, s[0:1]
	s_and_b64 s[0:1], s[0:1], s[52:53]
	v_cmp_gt_i32_e64 s[48:49], 41, v1
	v_cndmask_b32_e64 v87, v87, v175, s[0:1]
	s_and_b64 s[0:1], s[0:1], s[50:51]
	v_cmp_gt_i32_e64 s[46:47], 40, v1
	v_cndmask_b32_e64 v86, v86, v175, s[0:1]
	s_and_b64 s[0:1], s[0:1], s[48:49]
	v_cmp_gt_i32_e64 s[44:45], 35, v1
	v_cndmask_b32_e64 v73, v73, v175, s[0:1]
	s_and_b64 s[0:1], s[0:1], s[46:47]
	v_cmp_gt_i32_e64 s[42:43], 34, v1
	v_cndmask_b32_e64 v72, v72, v175, s[0:1]
	s_and_b64 s[0:1], s[0:1], s[44:45]
	v_cmp_gt_i32_e64 s[40:41], 33, v1
	v_cndmask_b32_e64 v85, v85, v175, s[0:1]
	s_and_b64 s[0:1], s[0:1], s[42:43]
	v_cmp_gt_i32_e32 vcc, 32, v1
	v_cndmask_b32_e64 v84, v84, v175, s[0:1]
	s_and_b64 s[0:1], s[0:1], s[40:41]
	v_cndmask_b32_e64 v74, v74, v175, s[88:89]
	v_readlane_b32 s88, v242, 2
	s_and_b64 vcc, s[0:1], vcc
	v_cndmask_b32_e64 v81, v81, v175, s[94:95]
	v_cndmask_b32_e64 v80, v80, v175, s[92:93]
	s_movk_i32 s93, 0x6018
	s_mov_b32 s92, 0xf800000
	v_cndmask_b32_e64 v75, v75, v175, s[90:91]
	s_mov_b64 s[90:91], s[16:17]
	v_readlane_b32 s89, v242, 3
	v_cndmask_b32_e64 v107, v107, v175, s[86:87]
	v_readlane_b32 s86, v242, 0
	v_cndmask_b32_e64 v106, v106, v175, s[84:85]
	v_cndmask_b32_e64 v79, v79, v175, s[82:83]
	s_movk_i32 s83, 0x6000
	v_cndmask_b32_e64 v78, v78, v175, s[80:81]
	v_cndmask_b32_e64 v105, v105, v175, s[78:79]
	v_cndmask_b32_e64 v104, v104, v175, s[76:77]
	v_cndmask_b32_e64 v103, v103, v175, s[74:75]
	v_cndmask_b32_e64 v102, v102, v175, s[72:73]
	v_cndmask_b32_e64 v101, v101, v175, s[70:71]
	v_cndmask_b32_e64 v100, v100, v175, s[68:69]
	v_cndmask_b32_e64 v99, v99, v175, s[2:3]
	s_mov_b32 s56, s30
	v_cndmask_b32_e64 v83, v83, v175, s[0:1]
	v_cndmask_b32_e32 v82, v82, v175, vcc
	v_readlane_b32 s87, v242, 1

.LBB0_653:
	v_sub_f32_e32 v104, v82, v1
	v_sub_f32_e32 v105, v83, v1
	v_sub_f32_e32 v208, v84, v1
	v_sub_f32_e32 v209, v85, v1
	v_sub_f32_e32 v210, v72, v1
	v_sub_f32_e32 v211, v73, v1
	v_sub_f32_e32 v212, v86, v1
	v_sub_f32_e32 v213, v87, v1
	v_sub_f32_e32 v214, v68, v1
	v_sub_f32_e32 v215, v69, v1
	v_sub_f32_e32 v216, v76, v1
	v_sub_f32_e32 v217, v77, v1
	v_sub_f32_e32 v218, v66, v1
	v_sub_f32_e32 v219, v67, v1
	v_sub_f32_e32 v220, v70, v1
	v_sub_f32_e32 v221, v71, v1
	s_waitcnt lgkmcnt(0)
	s_sub_i32 s0, s11, s27
	s_cmp_ge_i32 s0, 31
	s_cbranch_scc1 .Lmskip_fox_2
	ds_read_b128 v[228:231], v191 offset:32768
	ds_read_b128 v[232:235], v190 offset:32768
	ds_read_b128 v[236:239], v191 offset:40960
	ds_read_b128 v[248:251], v190 offset:40960
	ds_read_b128 v[252:255], v189 offset:32768
	s_waitcnt lgkmcnt(4)
	v_mfma_f32_32x32x16_bf16 v[82:97], v[228:231], v[142:145], 0
	ds_read_b128 v[228:231], v189 offset:40960
	s_waitcnt lgkmcnt(4)
	v_mfma_f32_32x32x16_bf16 v[82:97], v[232:235], v[138:141], v[82:97]
	ds_read_b128 v[232:235], v188 offset:32768
	s_waitcnt lgkmcnt(4)
	v_mfma_f32_32x32x16_bf16 v[66:81], v[236:239], v[142:145], 0
	ds_read_b128 v[236:239], v188 offset:40960
	s_waitcnt lgkmcnt(4)
	v_mfma_f32_32x32x16_bf16 v[66:81], v[248:251], v[138:141], v[66:81]
	ds_read_b128 v[248:251], v191 offset:32896
	s_waitcnt lgkmcnt(4)
	v_mfma_f32_32x32x16_bf16 v[82:97], v[252:255], v[134:137], v[82:97]
	ds_read_b128 v[252:255], v191 offset:41088
	s_waitcnt lgkmcnt(4)
	v_mfma_f32_32x32x16_bf16 v[66:81], v[228:231], v[134:137], v[66:81]
	ds_read_b128 v[228:231], v190 offset:32896
	s_waitcnt lgkmcnt(4)
	v_mfma_f32_32x32x16_bf16 v[82:97], v[232:235], v[130:133], v[82:97]
	ds_read_b128 v[232:235], v190 offset:41088
	s_waitcnt lgkmcnt(4)
	v_mfma_f32_32x32x16_bf16 v[66:81], v[236:239], v[130:133], v[66:81]
	ds_read_b128 v[236:239], v189 offset:32896
	s_waitcnt lgkmcnt(4)
	v_mfma_f32_32x32x16_bf16 v[82:97], v[248:251], v[126:129], v[82:97]
	ds_read_b128 v[248:251], v189 offset:41088
	s_waitcnt lgkmcnt(4)
	v_mfma_f32_32x32x16_bf16 v[66:81], v[252:255], v[126:129], v[66:81]
	ds_read_b128 v[252:255], v188 offset:32896
	s_waitcnt lgkmcnt(4)
	v_mfma_f32_32x32x16_bf16 v[82:97], v[228:231], v[122:125], v[82:97]
	ds_read_b128 v[228:231], v188 offset:41088
	s_waitcnt lgkmcnt(4)
	v_mfma_f32_32x32x16_bf16 v[66:81], v[232:235], v[122:125], v[66:81]
	s_waitcnt lgkmcnt(3)
	v_mfma_f32_32x32x16_bf16 v[82:97], v[236:239], v[118:121], v[82:97]
	s_waitcnt lgkmcnt(2)
	v_mfma_f32_32x32x16_bf16 v[66:81], v[248:251], v[118:121], v[66:81]
	s_waitcnt lgkmcnt(1)
	v_mfma_f32_32x32x16_bf16 v[82:97], v[252:255], v[114:117], v[82:97]
	s_waitcnt lgkmcnt(0)
	v_mfma_f32_32x32x16_bf16 v[66:81], v[228:231], v[114:117], v[66:81]
.Lmskip_fox_2:
	v_exp_f32_e32 v222, v104
	v_add_f32_e32 v104, 0, v196
	v_add_f32_e32 v104, v203, v104
	v_add_f32_e32 v104, v112, v104
	v_add_f32_e32 v104, v202, v104
	v_add_f32_e32 v104, v110, v104
	v_add_f32_e32 v104, v113, v104
	v_add_f32_e32 v104, v109, v104
	v_add_f32_e32 v104, v111, v104
	v_add_f32_e32 v104, v103, v104
	v_add_f32_e32 v104, v107, v104
	v_add_f32_e32 v104, v101, v104
	v_add_f32_e32 v104, v106, v104
	v_add_f32_e32 v104, v99, v104
	v_exp_f32_e32 v223, v105
	v_add_f32_e32 v104, v102, v104
	v_exp_f32_e32 v208, v208
	v_add_f32_e32 v104, v98, v104
	v_exp_f32_e32 v209, v209
	v_add_f32_e32 v104, v100, v104
	v_exp_f32_e32 v210, v210
	v_add_f32_e32 v104, v222, v104
	v_exp_f32_e32 v211, v211
	v_add_f32_e32 v104, v223, v104
	v_exp_f32_e32 v212, v212
	v_add_f32_e32 v104, v208, v104
	v_exp_f32_e32 v213, v213
	v_add_f32_e32 v104, v209, v104
	v_exp_f32_e32 v214, v214
	v_add_f32_e32 v104, v210, v104
	v_exp_f32_e32 v215, v215
	v_add_f32_e32 v104, v211, v104
	v_exp_f32_e32 v216, v216
	v_add_f32_e32 v104, v212, v104
	v_exp_f32_e32 v217, v217
	v_add_f32_e32 v104, v213, v104
	v_exp_f32_e32 v218, v218
	v_add_f32_e32 v104, v214, v104
	v_exp_f32_e32 v219, v219
	v_add_f32_e32 v104, v215, v104
	v_exp_f32_e32 v220, v220
	v_add_f32_e32 v104, v216, v104
	v_exp_f32_e32 v221, v221
	v_add_f32_e32 v104, v217, v104
	v_add_f32_e32 v104, v218, v104
	v_add_f32_e32 v104, v219, v104
	v_add_f32_e32 v104, v220, v104
	v_add_f32_e32 v104, v221, v104
	v_mov_b32_e32 v105, v104
	v_cvt_pk_bf16_f32 v204, v196, v203
	v_cvt_pk_bf16_f32 v205, v112, v202
	v_cvt_pk_bf16_f32 v206, v110, v113
	v_cvt_pk_bf16_f32 v207, v109, v111
	v_cvt_pk_bf16_f32 v110, v103, v107
	v_cvt_pk_bf16_f32 v111, v101, v106
	v_cvt_pk_bf16_f32 v112, v99, v102
	v_cvt_pk_bf16_f32 v113, v98, v100
	v_cvt_pk_bf16_f32 v98, v222, v223
	v_cvt_pk_bf16_f32 v99, v208, v209
	v_cvt_pk_bf16_f32 v100, v210, v211
	v_cvt_pk_bf16_f32 v101, v212, v213
	s_nop 1
	v_permlane32_swap_b32_e32 v104, v105
	v_permlane32_swap_b32_e32 v98, v100
	v_permlane32_swap_b32_e32 v99, v101
	v_cvt_pk_bf16_f32 v208, v214, v215
	v_cvt_pk_bf16_f32 v209, v216, v217
	v_cvt_pk_bf16_f32 v210, v218, v219
	v_cvt_pk_bf16_f32 v211, v220, v221
	v_permlane32_swap_b32_e32 v204, v206
	v_permlane32_swap_b32_e32 v205, v207
	v_permlane32_swap_b32_e32 v110, v112
	v_permlane32_swap_b32_e32 v111, v113
	v_permlane32_swap_b32_e32 v208, v210
	v_permlane32_swap_b32_e32 v209, v211
	s_waitcnt lgkmcnt(0)
	s_sub_i32 s0, s11, s27
	s_cmp_ge_i32 s0, 95
	s_cbranch_scc1 .Lmskip_fox_3
	ds_read_b64_tr_b16 v[212:213], v183 offset:0x4000
	ds_read_b64_tr_b16 v[214:215], v183 offset:0x4800
	ds_read_b64_tr_b16 v[216:217], v183 offset:0x5000
	ds_read_b64_tr_b16 v[218:219], v183 offset:0x5800
	ds_read_b64_tr_b16 v[220:221], v183 offset:0x6000
	ds_read_b64_tr_b16 v[222:223], v183 offset:0x6800
	ds_read_b64_tr_b16 v[224:225], v183 offset:0x7000
	ds_read_b64_tr_b16 v[226:227], v183 offset:0x7800
	s_nop 0
	s_waitcnt lgkmcnt(6)
	v_mfma_f32_32x32x16_bf16 v[50:65], v[204:207], v[212:215], v[50:65]
	ds_read_b64_tr_b16 v[212:213], v183 offset:0x4200
	ds_read_b64_tr_b16 v[214:215], v183 offset:0x4a00
	s_waitcnt lgkmcnt(6)
	v_mfma_f32_32x32x16_bf16 v[50:65], v[110:113], v[216:219], v[50:65]
	ds_read_b64_tr_b16 v[216:217], v183 offset:0x5200
	ds_read_b64_tr_b16 v[218:219], v183 offset:0x5a00
	s_waitcnt lgkmcnt(6)
	v_mfma_f32_32x32x16_bf16 v[50:65], v[98:101], v[220:223], v[50:65]
	ds_read_b64_tr_b16 v[220:221], v183 offset:0x6200
	ds_read_b64_tr_b16 v[222:223], v183 offset:0x6a00
	s_waitcnt lgkmcnt(6)
	v_mfma_f32_32x32x16_bf16 v[50:65], v[208:211], v[224:227], v[50:65]
	ds_read_b64_tr_b16 v[224:225], v183 offset:0x7200
	ds_read_b64_tr_b16 v[226:227], v183 offset:0x7a00
	s_waitcnt lgkmcnt(6)
	v_mfma_f32_32x32x16_bf16 v[34:49], v[204:207], v[212:215], v[34:49]
	ds_read_b64_tr_b16 v[212:213], v183 offset:0x4400
	ds_read_b64_tr_b16 v[214:215], v183 offset:0x4c00
	s_waitcnt lgkmcnt(6)
	v_mfma_f32_32x32x16_bf16 v[34:49], v[110:113], v[216:219], v[34:49]
	ds_read_b64_tr_b16 v[216:217], v183 offset:0x5400
	ds_read_b64_tr_b16 v[218:219], v183 offset:0x5c00
	s_waitcnt lgkmcnt(6)
	v_mfma_f32_32x32x16_bf16 v[34:49], v[98:101], v[220:223], v[34:49]
	ds_read_b64_tr_b16 v[220:221], v183 offset:0x6400
	ds_read_b64_tr_b16 v[222:223], v183 offset:0x6c00
	s_waitcnt lgkmcnt(6)
	v_mfma_f32_32x32x16_bf16 v[34:49], v[208:211], v[224:227], v[34:49]
	ds_read_b64_tr_b16 v[224:225], v183 offset:0x7400
	ds_read_b64_tr_b16 v[226:227], v183 offset:0x7c00
	s_waitcnt lgkmcnt(6)
	v_mfma_f32_32x32x16_bf16 v[18:33], v[204:207], v[212:215], v[18:33]
	ds_read_b64_tr_b16 v[212:213], v183 offset:0x4600
	ds_read_b64_tr_b16 v[214:215], v183 offset:0x4e00
	s_waitcnt lgkmcnt(6)
	v_mfma_f32_32x32x16_bf16 v[18:33], v[110:113], v[216:219], v[18:33]
	ds_read_b64_tr_b16 v[216:217], v183 offset:0x5600
	ds_read_b64_tr_b16 v[218:219], v183 offset:0x5e00
	s_waitcnt lgkmcnt(6)
	v_mfma_f32_32x32x16_bf16 v[18:33], v[98:101], v[220:223], v[18:33]
	ds_read_b64_tr_b16 v[220:221], v183 offset:0x6600
	ds_read_b64_tr_b16 v[222:223], v183 offset:0x6e00
	s_waitcnt lgkmcnt(6)
	v_mfma_f32_32x32x16_bf16 v[18:33], v[208:211], v[224:227], v[18:33]
	ds_read_b64_tr_b16 v[224:225], v183 offset:0x7600
	ds_read_b64_tr_b16 v[226:227], v183 offset:0x7e00
	s_waitcnt lgkmcnt(6)
	v_mfma_f32_32x32x16_bf16 v[2:17], v[204:207], v[212:215], v[2:17]
	s_waitcnt lgkmcnt(4)
	v_mfma_f32_32x32x16_bf16 v[2:17], v[110:113], v[216:219], v[2:17]
	s_waitcnt lgkmcnt(2)
	v_mfma_f32_32x32x16_bf16 v[2:17], v[98:101], v[220:223], v[2:17]
	s_waitcnt lgkmcnt(0)
	v_mfma_f32_32x32x16_bf16 v[2:17], v[208:211], v[224:227], v[2:17]
.Lmskip_fox_3:
	ds_read_b128 v[100:103], v198 offset:256
	ds_read_b128 v[110:113], v198 offset:288
	ds_read_b128 v[202:205], v198 offset:384
	ds_read_b128 v[206:209], v198 offset:416
	ds_read_b128 v[210:213], v198 offset:320
	ds_read_b128 v[214:217], v198 offset:352
	ds_read_b128 v[218:221], v198 offset:448
	ds_read_b128 v[222:225], v198 offset:480
	s_waitcnt lgkmcnt(7)
	v_xor_b32_e32 v103, 0x80000000, v103
	v_xor_b32_e32 v102, 0x80000000, v102
	s_waitcnt lgkmcnt(6)
	v_xor_b32_e32 v107, 0x80000000, v113
	v_xor_b32_e32 v106, 0x80000000, v112
	s_waitcnt lgkmcnt(3)
	v_xor_b32_e32 v113, 0x80000000, v213
	v_xor_b32_e32 v112, 0x80000000, v212
	s_waitcnt lgkmcnt(2)
	v_xor_b32_e32 v213, 0x80000000, v217
	v_xor_b32_e32 v212, 0x80000000, v216
	v_fma_f32 v98, v86, s12, -v110
	v_fma_f32 v99, v87, s12, -v111
	v_fma_f32 v86, v96, s12, v212
	v_fma_f32 v87, v97, s12, v213
	v_fma_f32 v88, v88, s12, v106
	v_fma_f32 v89, v89, s12, v107
	v_fma_f32 v84, v84, s12, v102
	v_fma_f32 v85, v85, s12, v103
	v_fma_f32 v96, v82, s12, -v100
	v_fma_f32 v97, v83, s12, -v101
	v_xor_b32_e32 v103, 0x80000000, v205
	v_xor_b32_e32 v102, 0x80000000, v204
	v_xor_b32_e32 v101, 0x80000000, v209
	v_xor_b32_e32 v100, 0x80000000, v208
	s_waitcnt lgkmcnt(1)
	v_xor_b32_e32 v107, 0x80000000, v221
	v_xor_b32_e32 v106, 0x80000000, v220
	s_waitcnt lgkmcnt(0)
	v_xor_b32_e32 v111, 0x80000000, v225
	v_xor_b32_e32 v110, 0x80000000, v224
	s_add_i32 s0, s11, 64
	v_fma_f32 v94, v94, s12, -v214
	v_fma_f32 v95, v95, s12, -v215
	v_fma_f32 v90, v90, s12, -v210
	v_fma_f32 v91, v91, s12, -v211
	v_fma_f32 v92, v92, s12, v112
	v_fma_f32 v93, v93, s12, v113
	v_fma_f32 v82, v78, s12, -v222
	v_fma_f32 v83, v79, s12, -v223
	v_fma_f32 v74, v74, s12, -v218
	v_fma_f32 v75, v75, s12, -v219
	v_fma_f32 v78, v70, s12, -v206
	v_fma_f32 v79, v71, s12, -v207
	v_fma_f32 v70, v80, s12, v110
	v_fma_f32 v71, v81, s12, v111
	v_fma_f32 v76, v76, s12, v106
	v_fma_f32 v77, v77, s12, v107
	v_fma_f32 v100, v72, s12, v100
	v_fma_f32 v101, v73, s12, v101
	v_fma_f32 v102, v68, s12, v102
	v_fma_f32 v103, v69, s12, v103
	s_cmp_le_i32 s0, s27
	v_fma_f32 v80, v66, s12, -v202
	v_fma_f32 v81, v67, s12, -v203
	s_cbranch_scc1 .LBB0_655
	v_cmp_gt_i32_e64 s[92:93], 26, v199
	v_cmp_gt_i32_e64 s[94:95], 27, v199
	v_cmp_gt_i32_e64 s[90:91], 25, v199
	s_and_b64 s[92:93], s[94:95], s[92:93]
	v_cmp_gt_i32_e64 s[88:89], 24, v199
	s_and_b64 s[90:91], s[92:93], s[90:91]
	v_cmp_gt_i32_e64 s[86:87], 19, v199
	s_and_b64 s[88:89], s[90:91], s[88:89]
	v_cmp_gt_i32_e64 s[84:85], 18, v199
	s_and_b64 s[86:87], s[88:89], s[86:87]
	v_cmp_gt_i32_e64 s[82:83], 17, v199
	s_and_b64 s[84:85], s[86:87], s[84:85]
	v_cmp_gt_i32_e64 s[80:81], 16, v199
	s_and_b64 s[82:83], s[84:85], s[82:83]
	v_cmp_gt_i32_e64 s[78:79], 11, v199
	s_and_b64 s[80:81], s[82:83], s[80:81]
	v_cmp_gt_i32_e64 s[76:77], 10, v199
	s_and_b64 s[78:79], s[80:81], s[78:79]
	v_cmp_gt_i32_e64 s[74:75], 9, v199
	s_and_b64 s[76:77], s[78:79], s[76:77]
	v_cmp_gt_i32_e64 s[72:73], 8, v199
	s_and_b64 s[74:75], s[76:77], s[74:75]
	v_cmp_gt_i32_e64 s[70:71], 3, v199
	s_and_b64 s[72:73], s[74:75], s[72:73]
	v_cmp_gt_i32_e64 s[68:69], 2, v199
	s_and_b64 s[70:71], s[72:73], s[70:71]
	v_cmp_gt_i32_e64 s[2:3], 1, v199
	s_and_b64 s[68:69], s[70:71], s[68:69]
	v_cmp_gt_i32_e64 s[0:1], 0, v199
	s_and_b64 s[2:3], s[68:69], s[2:3]
	s_and_b64 s[0:1], s[2:3], s[0:1]
	v_cmp_gt_i32_e64 s[66:67], 58, v199
	v_cndmask_b32_e64 v96, v96, v175, s[0:1]
	v_cmp_gt_i32_e64 s[0:1], 59, v199
	v_cmp_gt_i32_e64 s[64:65], 57, v199
	v_cmp_gt_i32_e64 s[62:63], 56, v199
	v_cndmask_b32_e64 v71, v71, v175, s[0:1]
	s_and_b64 s[0:1], s[0:1], s[66:67]
	v_cndmask_b32_e64 v70, v70, v175, s[0:1]
	s_and_b64 s[0:1], s[0:1], s[64:65]
	v_cmp_gt_i32_e64 s[60:61], 51, v199
	v_cndmask_b32_e64 v83, v83, v175, s[0:1]
	s_and_b64 s[0:1], s[0:1], s[62:63]
	v_cmp_gt_i32_e64 s[58:59], 50, v199
	v_cndmask_b32_e64 v82, v82, v175, s[0:1]
	s_and_b64 s[0:1], s[0:1], s[60:61]
	v_cmp_gt_i32_e64 s[56:57], 49, v199
	v_cndmask_b32_e64 v77, v77, v175, s[0:1]
	s_and_b64 s[0:1], s[0:1], s[58:59]
	v_cmp_gt_i32_e64 s[54:55], 48, v199
	v_cndmask_b32_e64 v76, v76, v175, s[0:1]
	s_and_b64 s[0:1], s[0:1], s[56:57]
	v_cmp_gt_i32_e64 s[52:53], 43, v199
	v_cndmask_b32_e64 v75, v75, v175, s[0:1]
	s_and_b64 s[0:1], s[0:1], s[54:55]
	v_cmp_gt_i32_e64 s[50:51], 42, v199
	v_cndmask_b32_e64 v74, v74, v175, s[0:1]
	s_and_b64 s[0:1], s[0:1], s[52:53]
	v_cmp_gt_i32_e64 s[48:49], 41, v199
	v_cndmask_b32_e64 v101, v101, v175, s[0:1]
	s_and_b64 s[0:1], s[0:1], s[50:51]
	v_cmp_gt_i32_e64 s[46:47], 40, v199
	v_cndmask_b32_e64 v100, v100, v175, s[0:1]
	s_and_b64 s[0:1], s[0:1], s[48:49]
	v_cmp_gt_i32_e64 s[44:45], 35, v199
	v_cndmask_b32_e64 v79, v79, v175, s[0:1]
	s_and_b64 s[0:1], s[0:1], s[46:47]
	v_cmp_gt_i32_e64 s[42:43], 34, v199
	v_cndmask_b32_e64 v78, v78, v175, s[0:1]
	s_and_b64 s[0:1], s[0:1], s[44:45]
	v_cmp_gt_i32_e64 s[40:41], 33, v199
	v_cndmask_b32_e64 v103, v103, v175, s[0:1]
	s_and_b64 s[0:1], s[0:1], s[42:43]
	v_cmp_gt_i32_e32 vcc, 32, v199
	v_cndmask_b32_e64 v102, v102, v175, s[0:1]
	s_and_b64 s[0:1], s[0:1], s[40:41]
	v_cndmask_b32_e64 v94, v94, v175, s[88:89]
	v_readlane_b32 s88, v242, 2
	s_and_b64 vcc, s[0:1], vcc
	v_cndmask_b32_e64 v87, v87, v175, s[94:95]
	v_cndmask_b32_e64 v86, v86, v175, s[92:93]
	s_movk_i32 s93, 0x6018
	s_mov_b32 s92, 0xf800000
	v_cndmask_b32_e64 v95, v95, v175, s[90:91]
	s_mov_b64 s[90:91], s[16:17]
	v_readlane_b32 s89, v242, 3
	v_cndmask_b32_e64 v93, v93, v175, s[86:87]
	v_readlane_b32 s86, v242, 0
	v_cndmask_b32_e64 v92, v92, v175, s[84:85]
	v_cndmask_b32_e64 v91, v91, v175, s[82:83]
	s_movk_i32 s83, 0x6000
	v_cndmask_b32_e64 v90, v90, v175, s[80:81]
	v_cndmask_b32_e64 v89, v89, v175, s[78:79]
	v_cndmask_b32_e64 v88, v88, v175, s[76:77]
	v_cndmask_b32_e64 v99, v99, v175, s[74:75]
	v_cndmask_b32_e64 v98, v98, v175, s[72:73]
	v_cndmask_b32_e64 v85, v85, v175, s[70:71]
	v_cndmask_b32_e64 v84, v84, v175, s[68:69]
	v_cndmask_b32_e64 v97, v97, v175, s[2:3]
	s_mov_b32 s56, s30
	v_cndmask_b32_e64 v81, v81, v175, s[0:1]
	v_cndmask_b32_e32 v80, v80, v175, vcc
	v_readlane_b32 s87, v242, 1

.LBB0_664:
	s_waitcnt vmcnt(0) lgkmcnt(0)
	s_lshl_b32 s9, s25, 6
	s_sub_i32 s9, s9, s27
	s_cmp_ge_i32 s9, 96
	s_cbranch_scc1 .Lmskip_fox_4
	ds_read_b128 v[82:85], v191 offset:49152
	ds_read_b128 v[86:89], v191 offset:57344
	s_waitcnt lgkmcnt(1)
	v_mfma_f32_32x32x16_bf16 v[98:113], v[82:85], v[142:145], 0
	s_waitcnt lgkmcnt(0)
	v_mfma_f32_32x32x16_bf16 v[82:97], v[86:89], v[142:145], 0
	ds_read_b128 v[142:145], v190 offset:49152
	s_waitcnt vmcnt(2)
	ds_read_b128 v[148:151], v190 offset:57344
	s_waitcnt lgkmcnt(1)
	v_mfma_f32_32x32x16_bf16 v[98:113], v[142:145], v[138:141], v[98:113]
	s_waitcnt lgkmcnt(0)
	v_mfma_f32_32x32x16_bf16 v[82:97], v[148:151], v[138:141], v[82:97]
	ds_read_b128 v[138:141], v189 offset:49152
	ds_read_b128 v[142:145], v189 offset:57344
	s_waitcnt lgkmcnt(1)
	v_mfma_f32_32x32x16_bf16 v[98:113], v[138:141], v[134:137], v[98:113]
	s_waitcnt lgkmcnt(0)
	v_mfma_f32_32x32x16_bf16 v[82:97], v[142:145], v[134:137], v[82:97]
	ds_read_b128 v[134:137], v188 offset:49152
	ds_read_b128 v[138:141], v188 offset:57344
	s_waitcnt lgkmcnt(1)
	v_mfma_f32_32x32x16_bf16 v[98:113], v[134:137], v[130:133], v[98:113]
	s_waitcnt lgkmcnt(0)
	v_mfma_f32_32x32x16_bf16 v[82:97], v[138:141], v[130:133], v[82:97]
	ds_read_b128 v[130:133], v191 offset:49280
	ds_read_b128 v[134:137], v191 offset:57472
	s_waitcnt lgkmcnt(1)
	v_mfma_f32_32x32x16_bf16 v[98:113], v[130:133], v[126:129], v[98:113]
	s_waitcnt lgkmcnt(0)
	v_mfma_f32_32x32x16_bf16 v[82:97], v[134:137], v[126:129], v[82:97]
	ds_read_b128 v[126:129], v190 offset:49280
	ds_read_b128 v[130:133], v190 offset:57472
	s_waitcnt lgkmcnt(1)
	v_mfma_f32_32x32x16_bf16 v[98:113], v[126:129], v[122:125], v[98:113]
	s_waitcnt lgkmcnt(0)
	v_mfma_f32_32x32x16_bf16 v[82:97], v[130:133], v[122:125], v[82:97]
	ds_read_b128 v[122:125], v189 offset:49280
	ds_read_b128 v[126:129], v189 offset:57472
	s_waitcnt lgkmcnt(1)
	v_mfma_f32_32x32x16_bf16 v[98:113], v[122:125], v[118:121], v[98:113]
	s_waitcnt lgkmcnt(0)
	v_mfma_f32_32x32x16_bf16 v[82:97], v[126:129], v[118:121], v[82:97]
	ds_read_b128 v[118:121], v188 offset:49280
	ds_read_b128 v[122:125], v188 offset:57472
	s_waitcnt lgkmcnt(1)
	v_mfma_f32_32x32x16_bf16 v[98:113], v[118:121], v[114:117], v[98:113]
	s_waitcnt lgkmcnt(0)
	v_mfma_f32_32x32x16_bf16 v[82:97], v[122:125], v[114:117], v[82:97]
.Lmskip_fox_4:
	v_exp_f32_e32 v81, v1
	v_add_f32_e32 v1, 0, v215
	v_add_f32_e32 v1, v217, v1
	v_add_f32_e32 v1, v213, v1
	v_add_f32_e32 v1, v216, v1
	v_add_f32_e32 v1, v211, v1
	v_add_f32_e32 v1, v214, v1
	v_add_f32_e32 v1, v210, v1
	v_add_f32_e32 v1, v212, v1
	v_add_f32_e32 v1, v207, v1
	v_add_f32_e32 v1, v209, v1
	v_add_f32_e32 v1, v205, v1
	v_add_f32_e32 v1, v208, v1
	v_exp_f32_e32 v80, v80
	v_add_f32_e32 v1, v203, v1
	v_add_f32_e32 v1, v206, v1
	v_exp_f32_e32 v78, v78
	v_add_f32_e32 v1, v202, v1
	v_exp_f32_e32 v79, v79
	v_add_f32_e32 v1, v204, v1
	v_exp_f32_e32 v76, v76
	v_add_f32_e32 v1, v80, v1
	v_exp_f32_e32 v77, v77
	v_add_f32_e32 v1, v81, v1
	v_exp_f32_e32 v115, v74
	v_add_f32_e32 v1, v78, v1
	v_exp_f32_e32 v116, v75
	v_add_f32_e32 v1, v79, v1
	v_exp_f32_e32 v117, v72
	v_add_f32_e32 v1, v76, v1
	v_exp_f32_e32 v118, v73
	v_add_f32_e32 v1, v77, v1
	v_exp_f32_e32 v119, v70
	v_add_f32_e32 v1, v115, v1
	v_exp_f32_e32 v120, v71
	v_add_f32_e32 v1, v116, v1
	v_exp_f32_e32 v121, v68
	v_add_f32_e32 v1, v117, v1
	v_exp_f32_e32 v122, v69
	v_add_f32_e32 v1, v118, v1
	v_exp_f32_e32 v123, v66
	v_add_f32_e32 v1, v119, v1
	v_exp_f32_e32 v124, v67
	v_add_f32_e32 v1, v120, v1
	v_add_f32_e32 v1, v121, v1
	v_add_f32_e32 v1, v122, v1
	v_add_f32_e32 v1, v123, v1
	v_add_f32_e32 v1, v124, v1
	v_mov_b32_e32 v114, v1
	v_cvt_pk_bf16_f32 v66, v215, v217
	v_cvt_pk_bf16_f32 v67, v213, v216
	v_cvt_pk_bf16_f32 v68, v211, v214
	v_cvt_pk_bf16_f32 v69, v210, v212
	v_cvt_pk_bf16_f32 v70, v207, v209
	v_cvt_pk_bf16_f32 v71, v205, v208
	v_cvt_pk_bf16_f32 v72, v203, v206
	v_cvt_pk_bf16_f32 v73, v202, v204
	v_cvt_pk_bf16_f32 v74, v80, v81
	v_cvt_pk_bf16_f32 v75, v78, v79
	v_cvt_pk_bf16_f32 v76, v76, v77
	v_cvt_pk_bf16_f32 v77, v115, v116
	v_cvt_pk_bf16_f32 v78, v117, v118
	v_cvt_pk_bf16_f32 v79, v119, v120
	v_cvt_pk_bf16_f32 v80, v121, v122
	v_cvt_pk_bf16_f32 v81, v123, v124
	s_nop 1
	v_permlane32_swap_b32_e32 v1, v114
	v_permlane32_swap_b32_e32 v66, v68
	v_permlane32_swap_b32_e32 v67, v69
	v_permlane32_swap_b32_e32 v70, v72
	v_permlane32_swap_b32_e32 v71, v73
	v_permlane32_swap_b32_e32 v74, v76
	v_permlane32_swap_b32_e32 v75, v77
	v_permlane32_swap_b32_e32 v78, v80
	v_permlane32_swap_b32_e32 v79, v81
	s_waitcnt vmcnt(0) lgkmcnt(0)
	s_cmp_ge_i32 s9, 160
	s_cbranch_scc1 .Lmskip_fox_5
	ds_read_b64_tr_b16 v[116:117], v183 offset:0
	ds_read_b64_tr_b16 v[118:119], v183 offset:0x800
	ds_read_b64_tr_b16 v[120:121], v183 offset:0x1000
	ds_read_b64_tr_b16 v[122:123], v183 offset:0x1800
	ds_read_b64_tr_b16 v[124:125], v183 offset:0x2000
	ds_read_b64_tr_b16 v[126:127], v183 offset:0x2800
	ds_read_b64_tr_b16 v[128:129], v183 offset:0x3000
	ds_read_b64_tr_b16 v[130:131], v183 offset:0x3800
	s_nop 0
	s_waitcnt lgkmcnt(6)
	v_mfma_f32_32x32x16_bf16 v[50:65], v[66:69], v[116:119], v[50:65]
	ds_read_b64_tr_b16 v[116:117], v183 offset:0x200
	ds_read_b64_tr_b16 v[118:119], v183 offset:0xa00
	s_waitcnt lgkmcnt(6)
	v_mfma_f32_32x32x16_bf16 v[50:65], v[70:73], v[120:123], v[50:65]
	ds_read_b64_tr_b16 v[120:121], v183 offset:0x1200
	ds_read_b64_tr_b16 v[122:123], v183 offset:0x1a00
	s_waitcnt lgkmcnt(6)
	v_mfma_f32_32x32x16_bf16 v[50:65], v[74:77], v[124:127], v[50:65]
	ds_read_b64_tr_b16 v[124:125], v183 offset:0x2200
	ds_read_b64_tr_b16 v[126:127], v183 offset:0x2a00
	s_waitcnt lgkmcnt(6)
	v_mfma_f32_32x32x16_bf16 v[50:65], v[78:81], v[128:131], v[50:65]
	ds_read_b64_tr_b16 v[128:129], v183 offset:0x3200
	ds_read_b64_tr_b16 v[130:131], v183 offset:0x3a00
	s_waitcnt lgkmcnt(6)
	v_mfma_f32_32x32x16_bf16 v[34:49], v[66:69], v[116:119], v[34:49]
	ds_read_b64_tr_b16 v[116:117], v183 offset:0x400
	ds_read_b64_tr_b16 v[118:119], v183 offset:0xc00
	s_waitcnt lgkmcnt(6)
	v_mfma_f32_32x32x16_bf16 v[34:49], v[70:73], v[120:123], v[34:49]
	ds_read_b64_tr_b16 v[120:121], v183 offset:0x1400
	ds_read_b64_tr_b16 v[122:123], v183 offset:0x1c00
	s_waitcnt lgkmcnt(6)
	v_mfma_f32_32x32x16_bf16 v[34:49], v[74:77], v[124:127], v[34:49]
	ds_read_b64_tr_b16 v[124:125], v183 offset:0x2400
	ds_read_b64_tr_b16 v[126:127], v183 offset:0x2c00
	s_waitcnt lgkmcnt(6)
	v_mfma_f32_32x32x16_bf16 v[34:49], v[78:81], v[128:131], v[34:49]
	ds_read_b64_tr_b16 v[128:129], v183 offset:0x3400
	ds_read_b64_tr_b16 v[130:131], v183 offset:0x3c00
	s_waitcnt lgkmcnt(6)
	v_mfma_f32_32x32x16_bf16 v[18:33], v[66:69], v[116:119], v[18:33]
	ds_read_b64_tr_b16 v[116:117], v183 offset:0x600
	ds_read_b64_tr_b16 v[118:119], v183 offset:0xe00
	s_waitcnt lgkmcnt(6)
	v_mfma_f32_32x32x16_bf16 v[18:33], v[70:73], v[120:123], v[18:33]
	ds_read_b64_tr_b16 v[120:121], v183 offset:0x1600
	ds_read_b64_tr_b16 v[122:123], v183 offset:0x1e00
	s_waitcnt lgkmcnt(6)
	v_mfma_f32_32x32x16_bf16 v[18:33], v[74:77], v[124:127], v[18:33]
	ds_read_b64_tr_b16 v[124:125], v183 offset:0x2600
	ds_read_b64_tr_b16 v[126:127], v183 offset:0x2e00
	s_waitcnt lgkmcnt(6)
	v_mfma_f32_32x32x16_bf16 v[18:33], v[78:81], v[128:131], v[18:33]
	ds_read_b64_tr_b16 v[128:129], v183 offset:0x3600
	ds_read_b64_tr_b16 v[130:131], v183 offset:0x3e00
	s_waitcnt lgkmcnt(6)
	v_mfma_f32_32x32x16_bf16 v[2:17], v[66:69], v[116:119], v[2:17]
	s_waitcnt lgkmcnt(4)
	v_mfma_f32_32x32x16_bf16 v[2:17], v[70:73], v[120:123], v[2:17]
	s_waitcnt lgkmcnt(2)
	v_mfma_f32_32x32x16_bf16 v[2:17], v[74:77], v[124:127], v[2:17]
	s_waitcnt lgkmcnt(0)
	v_mfma_f32_32x32x16_bf16 v[2:17], v[78:81], v[128:131], v[2:17]
.Lmskip_fox_5:
	s_lshl_b32 s1, s25, 6
	s_sub_i32 s0, s1, 64
	s_lshl_b32 s2, s0, 2
	s_add_i32 s2, s2, 0
	v_lshl_add_u32 v66, v186, 2, s2
	v_add_u32_e32 v66, 0x10800, v66
	s_add_i32 s1, s1, -1
	s_cmp_gt_i32 s1, s27
	ds_read_b128 v[116:119], v66 offset:128
	ds_read_b128 v[120:123], v66
	ds_read_b128 v[68:71], v66 offset:32
	ds_read_b128 v[124:127], v66 offset:160
	ds_read_b128 v[72:75], v66 offset:64
	ds_read_b128 v[128:131], v66 offset:192
	ds_read_b128 v[76:79], v66 offset:96
	ds_read_b128 v[132:135], v66 offset:224
	s_waitcnt lgkmcnt(6)
	v_xor_b32_e32 v81, 0x80000000, v123
	v_xor_b32_e32 v80, 0x80000000, v122
	s_waitcnt lgkmcnt(5)
	v_xor_b32_e32 v123, 0x80000000, v71
	v_xor_b32_e32 v122, 0x80000000, v70
	s_waitcnt lgkmcnt(1)
	v_xor_b32_e32 v79, 0x80000000, v79
	v_xor_b32_e32 v78, 0x80000000, v78
	v_xor_b32_e32 v137, 0x80000000, v75
	v_xor_b32_e32 v136, 0x80000000, v74
	v_fma_f32 v66, v110, s12, -v76
	v_fma_f32 v67, v111, s12, -v77
	v_fma_f32 v70, v106, s12, -v72
	v_fma_f32 v71, v107, s12, -v73
	v_fma_f32 v74, v102, s12, -v68
	v_fma_f32 v75, v103, s12, -v69
	v_fma_f32 v68, v112, s12, v78
	v_fma_f32 v69, v113, s12, v79
	v_fma_f32 v76, v104, s12, v122
	v_fma_f32 v77, v105, s12, v123
	v_fma_f32 v78, v100, s12, v80
	v_fma_f32 v79, v101, s12, v81
	v_xor_b32_e32 v101, 0x80000000, v119
	v_xor_b32_e32 v100, 0x80000000, v118
	v_xor_b32_e32 v103, 0x80000000, v127
	v_xor_b32_e32 v102, 0x80000000, v126
	v_xor_b32_e32 v105, 0x80000000, v131
	v_xor_b32_e32 v104, 0x80000000, v130
	s_waitcnt lgkmcnt(0)
	v_xor_b32_e32 v107, 0x80000000, v135
	v_xor_b32_e32 v106, 0x80000000, v134
	v_fma_f32 v72, v108, s12, v136
	v_fma_f32 v73, v109, s12, v137
	v_fma_f32 v80, v98, s12, -v120
	v_fma_f32 v81, v99, s12, -v121
	v_fma_f32 v94, v94, s12, -v132
	v_fma_f32 v95, v95, s12, -v133
	v_fma_f32 v90, v90, s12, -v128
	v_fma_f32 v91, v91, s12, -v129
	v_fma_f32 v98, v86, s12, -v124
	v_fma_f32 v99, v87, s12, -v125
	v_fma_f32 v86, v96, s12, v106
	v_fma_f32 v87, v97, s12, v107
	v_fma_f32 v92, v92, s12, v104
	v_fma_f32 v93, v93, s12, v105
	v_fma_f32 v88, v88, s12, v102
	v_fma_f32 v89, v89, s12, v103
	v_fma_f32 v84, v84, s12, v100
	v_fma_f32 v85, v85, s12, v101
	v_fma_f32 v82, v82, s12, -v116
	v_fma_f32 v83, v83, s12, -v117
	s_cbranch_scc0 .LBB0_666
	v_subrev_u32_e32 v96, s0, v187
	v_cmp_gt_i32_e64 s[92:93], 26, v96
	v_cmp_gt_i32_e64 s[94:95], 27, v96
	v_cmp_gt_i32_e64 s[90:91], 25, v96
	s_and_b64 s[92:93], s[94:95], s[92:93]
	v_cmp_gt_i32_e64 s[88:89], 24, v96
	s_and_b64 s[90:91], s[92:93], s[90:91]
	v_cmp_gt_i32_e64 s[86:87], 19, v96
	s_and_b64 s[88:89], s[90:91], s[88:89]
	v_cmp_gt_i32_e64 s[84:85], 18, v96
	s_and_b64 s[86:87], s[88:89], s[86:87]
	v_cmp_gt_i32_e64 s[82:83], 17, v96
	s_and_b64 s[84:85], s[86:87], s[84:85]
	v_cmp_gt_i32_e64 s[80:81], 16, v96
	s_and_b64 s[82:83], s[84:85], s[82:83]
	v_cmp_gt_i32_e64 s[78:79], 11, v96
	s_and_b64 s[80:81], s[82:83], s[80:81]
	v_cmp_gt_i32_e64 s[76:77], 10, v96
	s_and_b64 s[78:79], s[80:81], s[78:79]
	v_cmp_gt_i32_e64 s[74:75], 9, v96
	s_and_b64 s[76:77], s[78:79], s[76:77]
	v_cmp_gt_i32_e64 s[72:73], 8, v96
	s_and_b64 s[74:75], s[76:77], s[74:75]
	v_cmp_gt_i32_e64 s[70:71], 3, v96
	s_and_b64 s[72:73], s[74:75], s[72:73]
	v_cmp_gt_i32_e64 s[68:69], 2, v96
	s_and_b64 s[70:71], s[72:73], s[70:71]
	v_cmp_gt_i32_e64 s[2:3], 1, v96
	s_and_b64 s[68:69], s[70:71], s[68:69]
	v_cmp_gt_i32_e64 s[0:1], 0, v96
	s_and_b64 s[2:3], s[68:69], s[2:3]
	s_and_b64 s[0:1], s[2:3], s[0:1]
	v_cmp_gt_i32_e64 s[66:67], 58, v96
	v_cndmask_b32_e64 v80, v80, v175, s[0:1]
	v_cmp_gt_i32_e64 s[0:1], 59, v96
	v_cmp_gt_i32_e64 s[64:65], 57, v96
	v_cmp_gt_i32_e64 s[62:63], 56, v96
	v_cndmask_b32_e64 v87, v87, v175, s[0:1]
	s_and_b64 s[0:1], s[0:1], s[66:67]
	v_cndmask_b32_e64 v86, v86, v175, s[0:1]
	s_and_b64 s[0:1], s[0:1], s[64:65]
	v_cmp_gt_i32_e64 s[60:61], 51, v96
	v_cndmask_b32_e64 v95, v95, v175, s[0:1]
	s_and_b64 s[0:1], s[0:1], s[62:63]
	v_cmp_gt_i32_e64 s[58:59], 50, v96
	v_cndmask_b32_e64 v94, v94, v175, s[0:1]
	s_and_b64 s[0:1], s[0:1], s[60:61]
	v_cmp_gt_i32_e64 s[56:57], 49, v96
	v_cndmask_b32_e64 v93, v93, v175, s[0:1]
	s_and_b64 s[0:1], s[0:1], s[58:59]
	v_cmp_gt_i32_e64 s[54:55], 48, v96
	v_cndmask_b32_e64 v92, v92, v175, s[0:1]
	s_and_b64 s[0:1], s[0:1], s[56:57]
	v_cmp_gt_i32_e64 s[52:53], 43, v96
	v_cndmask_b32_e64 v91, v91, v175, s[0:1]
	s_and_b64 s[0:1], s[0:1], s[54:55]
	v_cmp_gt_i32_e64 s[50:51], 42, v96
	v_cndmask_b32_e64 v90, v90, v175, s[0:1]
	s_and_b64 s[0:1], s[0:1], s[52:53]
	v_cmp_gt_i32_e64 s[48:49], 41, v96
	v_cndmask_b32_e64 v89, v89, v175, s[0:1]
	s_and_b64 s[0:1], s[0:1], s[50:51]
	v_cmp_gt_i32_e64 s[46:47], 40, v96
	v_cndmask_b32_e64 v88, v88, v175, s[0:1]
	s_and_b64 s[0:1], s[0:1], s[48:49]
	v_cmp_gt_i32_e64 s[44:45], 35, v96
	v_cndmask_b32_e64 v99, v99, v175, s[0:1]
	s_and_b64 s[0:1], s[0:1], s[46:47]
	v_cmp_gt_i32_e64 s[42:43], 34, v96
	v_cndmask_b32_e64 v98, v98, v175, s[0:1]
	s_and_b64 s[0:1], s[0:1], s[44:45]
	v_cmp_gt_i32_e64 s[40:41], 33, v96
	v_cndmask_b32_e64 v85, v85, v175, s[0:1]
	s_and_b64 s[0:1], s[0:1], s[42:43]
	v_cmp_gt_i32_e32 vcc, 32, v96
	v_cndmask_b32_e64 v84, v84, v175, s[0:1]
	s_and_b64 s[0:1], s[0:1], s[40:41]
	v_cndmask_b32_e64 v66, v66, v175, s[88:89]
	v_readlane_b32 s88, v242, 2
	s_and_b64 vcc, s[0:1], vcc
	v_cndmask_b32_e64 v69, v69, v175, s[94:95]
	v_cndmask_b32_e64 v68, v68, v175, s[92:93]
	s_movk_i32 s93, 0x6018
	s_mov_b32 s92, 0xf800000
	v_cndmask_b32_e64 v67, v67, v175, s[90:91]
	s_mov_b64 s[90:91], s[16:17]
	v_readlane_b32 s89, v242, 3
	v_cndmask_b32_e64 v73, v73, v175, s[86:87]
	v_readlane_b32 s86, v242, 0
	v_cndmask_b32_e64 v72, v72, v175, s[84:85]
	v_cndmask_b32_e64 v71, v71, v175, s[82:83]
	s_movk_i32 s83, 0x6000
	v_cndmask_b32_e64 v70, v70, v175, s[80:81]
	v_cndmask_b32_e64 v77, v77, v175, s[78:79]
	v_cndmask_b32_e64 v76, v76, v175, s[76:77]
	v_cndmask_b32_e64 v75, v75, v175, s[74:75]
	v_cndmask_b32_e64 v74, v74, v175, s[72:73]
	v_cndmask_b32_e64 v79, v79, v175, s[70:71]
	v_cndmask_b32_e64 v78, v78, v175, s[68:69]
	v_cndmask_b32_e64 v81, v81, v175, s[2:3]
	s_mov_b32 s56, s30
	v_cndmask_b32_e64 v83, v83, v175, s[0:1]
	v_cndmask_b32_e32 v82, v82, v175, vcc
	v_readlane_b32 s87, v242, 1

.LBB0_670:
	v_cndmask_b32_e64 v97, v97, v196, s[40:41]
	v_sub_f32_e32 v80, v80, v97
	v_sub_f32_e32 v81, v81, v97
	v_exp_f32_e32 v80, v80
	v_sub_f32_e32 v78, v78, v97
	v_exp_f32_e32 v81, v81
	v_sub_f32_e32 v79, v79, v97
	v_exp_f32_e32 v78, v78
	v_sub_f32_e32 v74, v74, v97
	v_sub_f32_e32 v66, v66, v97
	v_exp_f32_e32 v79, v79
	v_sub_f32_e32 v75, v75, v97
	v_exp_f32_e32 v74, v74
	v_exp_f32_e32 v102, v66
	v_add_f32_e32 v66, 0, v80
	v_sub_f32_e32 v76, v76, v97
	v_exp_f32_e32 v75, v75
	v_add_f32_e32 v66, v81, v66
	v_sub_f32_e32 v77, v77, v97
	v_exp_f32_e32 v76, v76
	v_add_f32_e32 v66, v78, v66
	v_sub_f32_e32 v70, v70, v97
	v_exp_f32_e32 v77, v77
	v_add_f32_e32 v66, v79, v66
	v_sub_f32_e32 v82, v82, v97
	v_sub_f32_e32 v83, v83, v97
	v_sub_f32_e32 v84, v84, v97
	v_sub_f32_e32 v85, v85, v97
	v_sub_f32_e32 v98, v98, v97
	v_sub_f32_e32 v99, v99, v97
	v_sub_f32_e32 v88, v88, v97
	v_sub_f32_e32 v89, v89, v97
	v_sub_f32_e32 v90, v90, v97
	v_sub_f32_e32 v71, v71, v97
	v_sub_f32_e32 v91, v91, v97
	v_sub_f32_e32 v72, v72, v97
	v_sub_f32_e32 v92, v92, v97
	v_sub_f32_e32 v73, v73, v97
	v_sub_f32_e32 v93, v93, v97
	v_sub_f32_e32 v94, v94, v97
	v_sub_f32_e32 v67, v67, v97
	v_sub_f32_e32 v95, v95, v97
	v_sub_f32_e32 v68, v68, v97
	v_sub_f32_e32 v86, v86, v97
	v_sub_f32_e32 v69, v69, v97
	v_sub_f32_e32 v87, v87, v97
	v_exp_f32_e32 v97, v70
	v_add_f32_e32 v66, v74, v66
	v_exp_f32_e32 v100, v71
	v_add_f32_e32 v66, v75, v66
	v_exp_f32_e32 v101, v72
	v_add_f32_e32 v66, v76, v66
	v_exp_f32_e32 v73, v73
	v_add_f32_e32 v66, v77, v66
	v_add_f32_e32 v66, v97, v66
	v_exp_f32_e32 v103, v67
	v_add_f32_e32 v66, v100, v66
	v_exp_f32_e32 v104, v68
	v_add_f32_e32 v66, v101, v66
	v_exp_f32_e32 v105, v69
	v_add_f32_e32 v66, v73, v66
	v_exp_f32_e32 v82, v82
	v_add_f32_e32 v66, v102, v66
	v_exp_f32_e32 v83, v83
	v_add_f32_e32 v66, v103, v66
	v_exp_f32_e32 v84, v84
	v_add_f32_e32 v66, v104, v66
	v_exp_f32_e32 v85, v85
	v_add_f32_e32 v66, v105, v66
	v_exp_f32_e32 v98, v98
	v_add_f32_e32 v66, v82, v66
	v_exp_f32_e32 v99, v99
	v_add_f32_e32 v66, v83, v66
	v_exp_f32_e32 v88, v88
	v_add_f32_e32 v66, v84, v66
	v_exp_f32_e32 v89, v89
	v_add_f32_e32 v66, v85, v66
	v_exp_f32_e32 v90, v90
	v_add_f32_e32 v66, v98, v66
	v_exp_f32_e32 v91, v91
	v_add_f32_e32 v66, v99, v66
	v_exp_f32_e32 v92, v92
	v_add_f32_e32 v66, v88, v66
	v_exp_f32_e32 v93, v93
	v_add_f32_e32 v66, v89, v66
	v_exp_f32_e32 v94, v94
	v_add_f32_e32 v66, v90, v66
	v_exp_f32_e32 v95, v95
	v_add_f32_e32 v66, v91, v66
	v_exp_f32_e32 v86, v86
	v_add_f32_e32 v66, v92, v66
	v_exp_f32_e32 v87, v87
	v_add_f32_e32 v66, v93, v66
	v_add_f32_e32 v66, v94, v66
	v_add_f32_e32 v66, v95, v66
	v_add_f32_e32 v66, v86, v66
	v_add_f32_e32 v66, v87, v66
	v_mov_b32_e32 v67, v66
	s_nop 1
	v_permlane32_swap_b32_e32 v66, v67
	v_cvt_pk_bf16_f32 v68, v80, v81
	v_cvt_pk_bf16_f32 v69, v78, v79
	v_cvt_pk_bf16_f32 v70, v74, v75
	v_cvt_pk_bf16_f32 v71, v76, v77
	v_cvt_pk_bf16_f32 v72, v97, v100
	v_cvt_pk_bf16_f32 v73, v101, v73
	v_cvt_pk_bf16_f32 v74, v102, v103
	v_cvt_pk_bf16_f32 v75, v104, v105
	v_cvt_pk_bf16_f32 v76, v82, v83
	v_cvt_pk_bf16_f32 v77, v84, v85
	v_cvt_pk_bf16_f32 v78, v98, v99
	v_cvt_pk_bf16_f32 v79, v88, v89
	v_cvt_pk_bf16_f32 v80, v90, v91
	v_cvt_pk_bf16_f32 v81, v92, v93
	v_cvt_pk_bf16_f32 v82, v94, v95
	v_cvt_pk_bf16_f32 v83, v86, v87
	s_nop 0
	v_permlane32_swap_b32_e32 v68, v70
	v_permlane32_swap_b32_e32 v69, v71
	v_permlane32_swap_b32_e32 v72, v74
	v_permlane32_swap_b32_e32 v73, v75
	v_permlane32_swap_b32_e32 v76, v78
	v_permlane32_swap_b32_e32 v77, v79
	v_permlane32_swap_b32_e32 v80, v82
	v_permlane32_swap_b32_e32 v81, v83
	s_waitcnt vmcnt(0) lgkmcnt(0)
	s_cmp_ge_i32 s9, 96
	s_cbranch_scc1 .Lmskip_fox_6
	ds_read_b64_tr_b16 v[84:85], v183 offset:0x4000
	ds_read_b64_tr_b16 v[86:87], v183 offset:0x4800
	ds_read_b64_tr_b16 v[88:89], v183 offset:0x5000
	ds_read_b64_tr_b16 v[90:91], v183 offset:0x5800
	ds_read_b64_tr_b16 v[92:93], v183 offset:0x6000
	ds_read_b64_tr_b16 v[94:95], v183 offset:0x6800
	ds_read_b64_tr_b16 v[98:99], v183 offset:0x7000
	ds_read_b64_tr_b16 v[100:101], v183 offset:0x7800
	s_nop 0
	s_waitcnt lgkmcnt(6)
	v_mfma_f32_32x32x16_bf16 v[50:65], v[68:71], v[84:87], v[50:65]
	ds_read_b64_tr_b16 v[84:85], v183 offset:0x4200
	ds_read_b64_tr_b16 v[86:87], v183 offset:0x4a00
	s_waitcnt lgkmcnt(6)
	v_mfma_f32_32x32x16_bf16 v[50:65], v[72:75], v[88:91], v[50:65]
	ds_read_b64_tr_b16 v[88:89], v183 offset:0x5200
	ds_read_b64_tr_b16 v[90:91], v183 offset:0x5a00
	s_waitcnt lgkmcnt(6)
	v_mfma_f32_32x32x16_bf16 v[50:65], v[76:79], v[92:95], v[50:65]
	ds_read_b64_tr_b16 v[92:93], v183 offset:0x6200
	ds_read_b64_tr_b16 v[94:95], v183 offset:0x6a00
	s_waitcnt lgkmcnt(6)
	v_mfma_f32_32x32x16_bf16 v[50:65], v[80:83], v[98:101], v[50:65]
	ds_read_b64_tr_b16 v[98:99], v183 offset:0x7200
	ds_read_b64_tr_b16 v[100:101], v183 offset:0x7a00
	s_waitcnt lgkmcnt(6)
	v_mfma_f32_32x32x16_bf16 v[34:49], v[68:71], v[84:87], v[34:49]
	ds_read_b64_tr_b16 v[84:85], v183 offset:0x4400
	ds_read_b64_tr_b16 v[86:87], v183 offset:0x4c00
	s_waitcnt lgkmcnt(6)
	v_mfma_f32_32x32x16_bf16 v[34:49], v[72:75], v[88:91], v[34:49]
	ds_read_b64_tr_b16 v[88:89], v183 offset:0x5400
	ds_read_b64_tr_b16 v[90:91], v183 offset:0x5c00
	s_waitcnt lgkmcnt(6)
	v_mfma_f32_32x32x16_bf16 v[34:49], v[76:79], v[92:95], v[34:49]
	ds_read_b64_tr_b16 v[92:93], v183 offset:0x6400
	ds_read_b64_tr_b16 v[94:95], v183 offset:0x6c00
	s_waitcnt lgkmcnt(6)
	v_mfma_f32_32x32x16_bf16 v[34:49], v[80:83], v[98:101], v[34:49]
	ds_read_b64_tr_b16 v[98:99], v183 offset:0x7400
	ds_read_b64_tr_b16 v[100:101], v183 offset:0x7c00
	s_waitcnt lgkmcnt(6)
	v_mfma_f32_32x32x16_bf16 v[18:33], v[68:71], v[84:87], v[18:33]
	ds_read_b64_tr_b16 v[84:85], v183 offset:0x4600
	ds_read_b64_tr_b16 v[86:87], v183 offset:0x4e00
	s_waitcnt lgkmcnt(6)
	v_mfma_f32_32x32x16_bf16 v[18:33], v[72:75], v[88:91], v[18:33]
	ds_read_b64_tr_b16 v[88:89], v183 offset:0x5600
	ds_read_b64_tr_b16 v[90:91], v183 offset:0x5e00
	s_waitcnt lgkmcnt(6)
	v_mfma_f32_32x32x16_bf16 v[18:33], v[76:79], v[92:95], v[18:33]
	ds_read_b64_tr_b16 v[92:93], v183 offset:0x6600
	ds_read_b64_tr_b16 v[94:95], v183 offset:0x6e00
	s_waitcnt lgkmcnt(6)
	v_mfma_f32_32x32x16_bf16 v[18:33], v[80:83], v[98:101], v[18:33]
	ds_read_b64_tr_b16 v[98:99], v183 offset:0x7600
	ds_read_b64_tr_b16 v[100:101], v183 offset:0x7e00
	s_waitcnt lgkmcnt(6)
	v_mfma_f32_32x32x16_bf16 v[2:17], v[68:71], v[84:87], v[2:17]
	s_waitcnt lgkmcnt(4)
	v_mfma_f32_32x32x16_bf16 v[2:17], v[72:75], v[88:91], v[2:17]
	s_waitcnt lgkmcnt(2)
	v_mfma_f32_32x32x16_bf16 v[2:17], v[76:79], v[92:95], v[2:17]
	s_waitcnt lgkmcnt(0)
	v_mfma_f32_32x32x16_bf16 v[2:17], v[80:83], v[98:101], v[2:17]
.Lmskip_fox_6:
	s_and_saveexec_b64 s[0:1], s[38:39]
	v_add_f32_e32 v1, v1, v114
	v_fmac_f32_e32 v1, v162, v146
	v_add_f32_e32 v66, v66, v67
	v_fmac_f32_e32 v66, v1, v96
	ds_write_b32 v185, v66
	s_or_b64 exec, exec, s[0:1]
	s_waitcnt lgkmcnt(0)
	ds_read_b128 v[78:81], v184
	ds_read_b128 v[74:77], v184 offset:32
	ds_read_b128 v[70:73], v184 offset:64
	ds_read_b128 v[66:69], v184 offset:96
	s_lshl_b32 s0, s5, 13
	s_waitcnt lgkmcnt(3)
	v_rcp_f32_e32 v78, v78
	v_and_b32_e32 v1, 1, v180
	s_add_i32 s2, s0, 0
	v_cmp_eq_u32_e32 vcc, 0, v1
	v_lshlrev_b32_e32 v1, 10, v181
	v_lshlrev_b32_e32 v82, 1, v182
	v_mul_f32_e32 v50, v50, v78
	v_add3_u32 v1, s2, v1, v82
	s_waitcnt lgkmcnt(0)
	v_mov_b32_dpp v82, v50 quad_perm:[1,0,3,2] row_mask:0xf bank_mask:0xf bound_ctrl:1
	s_barrier
	s_and_saveexec_b64 s[0:1], vcc
	s_cbranch_execz .LBB0_674
	v_cvt_pk_bf16_f32 v50, v50, v82
	ds_write_b32 v1, v50

.LBB0_823:
	v_add_u32_e32 v182, s9, v158
	v_add_u32_e32 v66, 1, v182
	v_mad_i64_i32 v[66:67], s[0:1], v66, s33, v[130:131]
	v_add_u32_e32 v68, 33, v182
	v_mad_i64_i32 v[68:69], s[0:1], v68, s33, v[130:131]
	global_load_dwordx4 v[114:117], v[66:67], off offset:2048
	global_load_dwordx4 v[122:125], v[66:67], off offset:1024
	global_load_dwordx4 v[118:121], v[68:69], off offset:2048
	global_load_dwordx4 v[126:129], v[68:69], off offset:1024
	s_waitcnt lgkmcnt(0)
	s_sub_i32 s0, s9, s25
	s_cmp_ge_i32 s0, 95
	s_cbranch_scc1 .Lmskip_dif_0
	ds_read_b128 v[228:231], v159 offset:49152
	ds_read_b128 v[232:235], v160 offset:49152
	ds_read_b128 v[236:239], v159 offset:57344
	ds_read_b128 v[248:251], v160 offset:57344
	ds_read_b128 v[252:255], v161 offset:49152
	s_waitcnt lgkmcnt(4)
	v_mfma_f32_32x32x16_bf16 v[82:97], v[228:231], v[110:113], 0
	ds_read_b128 v[228:231], v161 offset:57344
	s_waitcnt lgkmcnt(4)
	v_mfma_f32_32x32x16_bf16 v[82:97], v[232:235], v[106:109], v[82:97]
	ds_read_b128 v[232:235], v162 offset:49152
	s_waitcnt lgkmcnt(4)
	v_mfma_f32_32x32x16_bf16 v[66:81], v[236:239], v[110:113], 0
	ds_read_b128 v[236:239], v162 offset:57344
	s_waitcnt lgkmcnt(4)
	v_mfma_f32_32x32x16_bf16 v[66:81], v[248:251], v[106:109], v[66:81]
	s_waitcnt lgkmcnt(3)
	v_mfma_f32_32x32x16_bf16 v[82:97], v[252:255], v[102:105], v[82:97]
	s_waitcnt lgkmcnt(2)
	v_mfma_f32_32x32x16_bf16 v[66:81], v[228:231], v[102:105], v[66:81]
	s_waitcnt lgkmcnt(1)
	v_mfma_f32_32x32x16_bf16 v[82:97], v[232:235], v[98:101], v[82:97]
	s_waitcnt lgkmcnt(0)
	v_mfma_f32_32x32x16_bf16 v[66:81], v[236:239], v[98:101], v[66:81]
.Lmskip_dif_0:
	v_exp_f32_e32 v206, v132
	v_add_f32_e32 v132, 0, v197
	v_add_f32_e32 v132, v199, v132
	v_add_f32_e32 v132, v195, v132
	v_add_f32_e32 v132, v198, v132
	v_add_f32_e32 v132, v193, v132
	v_add_f32_e32 v132, v196, v132
	v_add_f32_e32 v132, v192, v132
	v_add_f32_e32 v132, v194, v132
	v_add_f32_e32 v132, v189, v132
	v_add_f32_e32 v132, v191, v132
	v_add_f32_e32 v132, v187, v132
	v_add_f32_e32 v132, v190, v132
	v_exp_f32_e32 v146, v146
	v_add_f32_e32 v132, v185, v132
	v_exp_f32_e32 v147, v147
	v_add_f32_e32 v132, v188, v132
	v_exp_f32_e32 v144, v144
	v_add_f32_e32 v132, v184, v132
	v_exp_f32_e32 v145, v145
	v_add_f32_e32 v132, v186, v132
	v_exp_f32_e32 v142, v142
	v_add_f32_e32 v132, v146, v132
	v_exp_f32_e32 v143, v143
	v_add_f32_e32 v132, v147, v132
	v_exp_f32_e32 v181, v140
	v_add_f32_e32 v132, v144, v132
	v_exp_f32_e32 v183, v141
	v_add_f32_e32 v132, v145, v132
	v_exp_f32_e32 v200, v138
	v_add_f32_e32 v132, v142, v132
	v_exp_f32_e32 v201, v139
	v_add_f32_e32 v132, v143, v132
	v_exp_f32_e32 v202, v136
	v_add_f32_e32 v132, v181, v132
	v_exp_f32_e32 v203, v137
	v_add_f32_e32 v132, v183, v132
	v_exp_f32_e32 v204, v134
	v_add_f32_e32 v132, v200, v132
	v_exp_f32_e32 v205, v135
	v_add_f32_e32 v132, v201, v132
	v_add_f32_e32 v132, v202, v132
	v_exp_f32_e32 v207, v133
	v_add_f32_e32 v132, v203, v132
	v_add_f32_e32 v132, v204, v132
	v_add_f32_e32 v132, v205, v132
	v_add_f32_e32 v132, v206, v132
	v_add_f32_e32 v179, v207, v132
	v_mov_b32_e32 v180, v179
	s_nop 1
	v_permlane32_swap_b32_e32 v179, v180
	v_cvt_pk_bf16_f32 v132, v197, v199
	v_cvt_pk_bf16_f32 v133, v195, v198
	v_cvt_pk_bf16_f32 v134, v193, v196
	v_cvt_pk_bf16_f32 v135, v192, v194
	v_cvt_pk_bf16_f32 v136, v189, v191
	v_cvt_pk_bf16_f32 v137, v187, v190
	v_cvt_pk_bf16_f32 v138, v185, v188
	v_cvt_pk_bf16_f32 v139, v184, v186
	v_cvt_pk_bf16_f32 v140, v146, v147
	v_cvt_pk_bf16_f32 v141, v144, v145
	v_cvt_pk_bf16_f32 v142, v142, v143
	v_cvt_pk_bf16_f32 v143, v181, v183
	v_cvt_pk_bf16_f32 v144, v200, v201
	v_cvt_pk_bf16_f32 v145, v202, v203
	v_cvt_pk_bf16_f32 v146, v204, v205
	v_cvt_pk_bf16_f32 v147, v206, v207
	s_nop 0
	v_permlane32_swap_b32_e32 v132, v134
	v_permlane32_swap_b32_e32 v133, v135
	v_permlane32_swap_b32_e32 v136, v138
	v_permlane32_swap_b32_e32 v137, v139
	v_permlane32_swap_b32_e32 v140, v142
	v_permlane32_swap_b32_e32 v141, v143
	v_permlane32_swap_b32_e32 v144, v146
	v_permlane32_swap_b32_e32 v145, v147
	s_waitcnt lgkmcnt(0)
	s_sub_i32 s0, s9, s25
	s_cmp_ge_i32 s0, 159
	s_cbranch_scc1 .Lmskip_dif_1
	ds_read_b64_tr_b16 v[184:185], v153 offset:0
	ds_read_b64_tr_b16 v[186:187], v153 offset:0x800
	ds_read_b64_tr_b16 v[188:189], v153 offset:0x1000
	ds_read_b64_tr_b16 v[190:191], v153 offset:0x1800
	ds_read_b64_tr_b16 v[192:193], v153 offset:0x2000
	ds_read_b64_tr_b16 v[194:195], v153 offset:0x2800
	ds_read_b64_tr_b16 v[196:197], v153 offset:0x3000
	ds_read_b64_tr_b16 v[198:199], v153 offset:0x3800
	s_nop 0
	s_waitcnt lgkmcnt(6)
	v_mfma_f32_32x32x16_bf16 v[50:65], v[132:135], v[184:187], v[50:65]
	ds_read_b64_tr_b16 v[184:185], v153 offset:0x200
	ds_read_b64_tr_b16 v[186:187], v153 offset:0xa00
	s_waitcnt lgkmcnt(6)
	v_mfma_f32_32x32x16_bf16 v[50:65], v[136:139], v[188:191], v[50:65]
	ds_read_b64_tr_b16 v[188:189], v153 offset:0x1200
	ds_read_b64_tr_b16 v[190:191], v153 offset:0x1a00
	s_waitcnt lgkmcnt(6)
	v_mfma_f32_32x32x16_bf16 v[50:65], v[140:143], v[192:195], v[50:65]
	ds_read_b64_tr_b16 v[192:193], v153 offset:0x2200
	ds_read_b64_tr_b16 v[194:195], v153 offset:0x2a00
	s_waitcnt lgkmcnt(6)
	v_mfma_f32_32x32x16_bf16 v[50:65], v[144:147], v[196:199], v[50:65]
	ds_read_b64_tr_b16 v[196:197], v153 offset:0x3200
	ds_read_b64_tr_b16 v[198:199], v153 offset:0x3a00
	s_waitcnt lgkmcnt(6)
	v_mfma_f32_32x32x16_bf16 v[34:49], v[132:135], v[184:187], v[34:49]
	ds_read_b64_tr_b16 v[184:185], v153 offset:0x400
	ds_read_b64_tr_b16 v[186:187], v153 offset:0xc00
	s_waitcnt lgkmcnt(6)
	v_mfma_f32_32x32x16_bf16 v[34:49], v[136:139], v[188:191], v[34:49]
	ds_read_b64_tr_b16 v[188:189], v153 offset:0x1400
	ds_read_b64_tr_b16 v[190:191], v153 offset:0x1c00
	s_waitcnt lgkmcnt(6)
	v_mfma_f32_32x32x16_bf16 v[34:49], v[140:143], v[192:195], v[34:49]
	ds_read_b64_tr_b16 v[192:193], v153 offset:0x2400
	ds_read_b64_tr_b16 v[194:195], v153 offset:0x2c00
	s_waitcnt lgkmcnt(6)
	v_mfma_f32_32x32x16_bf16 v[34:49], v[144:147], v[196:199], v[34:49]
	ds_read_b64_tr_b16 v[196:197], v153 offset:0x3400
	ds_read_b64_tr_b16 v[198:199], v153 offset:0x3c00
	s_waitcnt lgkmcnt(6)
	v_mfma_f32_32x32x16_bf16 v[18:33], v[132:135], v[184:187], v[18:33]
	ds_read_b64_tr_b16 v[184:185], v153 offset:0x600
	ds_read_b64_tr_b16 v[186:187], v153 offset:0xe00
	s_waitcnt lgkmcnt(6)
	v_mfma_f32_32x32x16_bf16 v[18:33], v[136:139], v[188:191], v[18:33]
	ds_read_b64_tr_b16 v[188:189], v153 offset:0x1600
	ds_read_b64_tr_b16 v[190:191], v153 offset:0x1e00
	s_waitcnt lgkmcnt(6)
	v_mfma_f32_32x32x16_bf16 v[18:33], v[140:143], v[192:195], v[18:33]
	ds_read_b64_tr_b16 v[192:193], v153 offset:0x2600
	ds_read_b64_tr_b16 v[194:195], v153 offset:0x2e00
	s_waitcnt lgkmcnt(6)
	v_mfma_f32_32x32x16_bf16 v[18:33], v[144:147], v[196:199], v[18:33]
	ds_read_b64_tr_b16 v[196:197], v153 offset:0x3600
	ds_read_b64_tr_b16 v[198:199], v153 offset:0x3e00
	s_waitcnt lgkmcnt(6)
	v_mfma_f32_32x32x16_bf16 v[2:17], v[132:135], v[184:187], v[2:17]
	s_waitcnt lgkmcnt(4)
	v_mfma_f32_32x32x16_bf16 v[2:17], v[136:139], v[188:191], v[2:17]
	s_waitcnt lgkmcnt(2)
	v_mfma_f32_32x32x16_bf16 v[2:17], v[140:143], v[192:195], v[2:17]
	s_waitcnt lgkmcnt(0)
	v_mfma_f32_32x32x16_bf16 v[2:17], v[144:147], v[196:199], v[2:17]
.Lmskip_dif_1:
	s_cmp_le_i32 s9, s25
	s_cbranch_scc1 .LBB0_825
	v_add_u32_e32 v132, 64, v169
	v_cmp_gt_i32_e64 s[92:93], 26, v132
	v_cmp_gt_i32_e64 s[94:95], 27, v132
	v_cmp_gt_i32_e64 s[90:91], 25, v132
	s_and_b64 s[92:93], s[94:95], s[92:93]
	v_cmp_gt_i32_e64 s[88:89], 24, v132
	s_and_b64 s[90:91], s[92:93], s[90:91]
	v_cmp_gt_i32_e64 s[86:87], 19, v132
	s_and_b64 s[88:89], s[90:91], s[88:89]
	v_cmp_gt_i32_e64 s[84:85], 18, v132
	s_and_b64 s[86:87], s[88:89], s[86:87]
	v_cmp_gt_i32_e64 s[82:83], 17, v132
	s_and_b64 s[84:85], s[86:87], s[84:85]
	v_cmp_gt_i32_e64 s[80:81], 16, v132
	s_and_b64 s[82:83], s[84:85], s[82:83]
	v_cmp_gt_i32_e64 s[78:79], 11, v132
	s_and_b64 s[80:81], s[82:83], s[80:81]
	v_cmp_gt_i32_e64 s[76:77], 10, v132
	s_and_b64 s[78:79], s[80:81], s[78:79]
	v_cmp_gt_i32_e64 s[74:75], 9, v132
	s_and_b64 s[76:77], s[78:79], s[76:77]
	v_cmp_gt_i32_e64 s[72:73], 8, v132
	s_and_b64 s[74:75], s[76:77], s[74:75]
	v_cmp_gt_i32_e64 s[70:71], 3, v132
	s_and_b64 s[72:73], s[74:75], s[72:73]
	v_cmp_gt_i32_e64 s[68:69], 2, v132
	s_and_b64 s[70:71], s[72:73], s[70:71]
	v_cmp_gt_i32_e64 s[2:3], 1, v132
	s_and_b64 s[68:69], s[70:71], s[68:69]
	v_cmp_gt_i32_e64 s[0:1], 0, v132
	s_and_b64 s[2:3], s[68:69], s[2:3]
	s_and_b64 s[0:1], s[2:3], s[0:1]
	v_cmp_gt_i32_e64 s[66:67], 58, v132
	v_cndmask_b32_e64 v82, v82, v175, s[0:1]
	v_cmp_gt_i32_e64 s[0:1], 59, v132
	v_cmp_gt_i32_e64 s[64:65], 57, v132
	v_cmp_gt_i32_e64 s[62:63], 56, v132
	v_cndmask_b32_e64 v81, v81, v175, s[0:1]
	s_and_b64 s[0:1], s[0:1], s[66:67]
	v_cndmask_b32_e64 v80, v80, v175, s[0:1]
	s_and_b64 s[0:1], s[0:1], s[64:65]
	v_cmp_gt_i32_e64 s[60:61], 51, v132
	v_cndmask_b32_e64 v79, v79, v175, s[0:1]
	s_and_b64 s[0:1], s[0:1], s[62:63]
	v_cmp_gt_i32_e64 s[58:59], 50, v132
	v_cndmask_b32_e64 v78, v78, v175, s[0:1]
	s_and_b64 s[0:1], s[0:1], s[60:61]
	v_cmp_gt_i32_e64 s[56:57], 49, v132
	v_cndmask_b32_e64 v77, v77, v175, s[0:1]
	s_and_b64 s[0:1], s[0:1], s[58:59]
	v_cmp_gt_i32_e64 s[54:55], 48, v132
	v_cndmask_b32_e64 v76, v76, v175, s[0:1]
	s_and_b64 s[0:1], s[0:1], s[56:57]
	v_cmp_gt_i32_e64 s[52:53], 43, v132
	v_cndmask_b32_e64 v75, v75, v175, s[0:1]
	s_and_b64 s[0:1], s[0:1], s[54:55]
	v_cmp_gt_i32_e64 s[50:51], 42, v132
	v_cndmask_b32_e64 v74, v74, v175, s[0:1]
	s_and_b64 s[0:1], s[0:1], s[52:53]
	v_cmp_gt_i32_e64 s[48:49], 41, v132
	v_cndmask_b32_e64 v73, v73, v175, s[0:1]
	s_and_b64 s[0:1], s[0:1], s[50:51]
	v_cmp_gt_i32_e64 s[46:47], 40, v132
	v_cndmask_b32_e64 v72, v72, v175, s[0:1]
	s_and_b64 s[0:1], s[0:1], s[48:49]
	v_cmp_gt_i32_e64 s[44:45], 35, v132
	v_cndmask_b32_e64 v71, v71, v175, s[0:1]
	s_and_b64 s[0:1], s[0:1], s[46:47]
	v_cmp_gt_i32_e64 s[42:43], 34, v132
	v_cndmask_b32_e64 v70, v70, v175, s[0:1]
	s_and_b64 s[0:1], s[0:1], s[44:45]
	v_cmp_gt_i32_e64 s[40:41], 33, v132
	v_cndmask_b32_e64 v69, v69, v175, s[0:1]
	s_and_b64 s[0:1], s[0:1], s[42:43]
	v_cmp_gt_i32_e32 vcc, 32, v132
	v_cndmask_b32_e64 v68, v68, v175, s[0:1]
	s_and_b64 s[0:1], s[0:1], s[40:41]
	s_and_b64 vcc, s[0:1], vcc
	v_cndmask_b32_e64 v97, v97, v175, s[94:95]
	v_cndmask_b32_e64 v96, v96, v175, s[92:93]
	v_cndmask_b32_e64 v95, v95, v175, s[90:91]
	v_cndmask_b32_e64 v94, v94, v175, s[88:89]
	v_cndmask_b32_e64 v93, v93, v175, s[86:87]
	v_cndmask_b32_e64 v92, v92, v175, s[84:85]
	v_cndmask_b32_e64 v91, v91, v175, s[82:83]
	v_cndmask_b32_e64 v90, v90, v175, s[80:81]
	v_cndmask_b32_e64 v89, v89, v175, s[78:79]
	v_cndmask_b32_e64 v88, v88, v175, s[76:77]
	v_cndmask_b32_e64 v87, v87, v175, s[74:75]
	v_cndmask_b32_e64 v86, v86, v175, s[72:73]
	v_cndmask_b32_e64 v85, v85, v175, s[70:71]
	v_cndmask_b32_e64 v84, v84, v175, s[68:69]
	v_cndmask_b32_e64 v83, v83, v175, s[2:3]
	v_cndmask_b32_e64 v67, v67, v175, s[0:1]
	v_cndmask_b32_e32 v66, v66, v175, vcc

.LBB0_831:
	s_waitcnt lgkmcnt(0)
	s_sub_i32 s0, s9, s25
	s_cmp_ge_i32 s0, 31
	s_cbranch_scc1 .Lmskip_dif_2
	ds_read_b128 v[228:231], v159 offset:32768
	ds_read_b128 v[232:235], v160 offset:32768
	ds_read_b128 v[236:239], v159 offset:40960
	ds_read_b128 v[248:251], v160 offset:40960
	ds_read_b128 v[252:255], v161 offset:32768
	s_waitcnt lgkmcnt(4)
	v_mfma_f32_32x32x16_bf16 v[82:97], v[228:231], v[110:113], 0
	ds_read_b128 v[228:231], v161 offset:40960
	s_waitcnt lgkmcnt(4)
	v_mfma_f32_32x32x16_bf16 v[82:97], v[232:235], v[106:109], v[82:97]
	ds_read_b128 v[232:235], v162 offset:32768
	s_waitcnt lgkmcnt(4)
	v_mfma_f32_32x32x16_bf16 v[66:81], v[236:239], v[110:113], 0
	ds_read_b128 v[236:239], v162 offset:40960
	s_waitcnt lgkmcnt(4)
	v_mfma_f32_32x32x16_bf16 v[66:81], v[248:251], v[106:109], v[66:81]
	s_waitcnt lgkmcnt(3)
	v_mfma_f32_32x32x16_bf16 v[82:97], v[252:255], v[102:105], v[82:97]
	s_waitcnt lgkmcnt(2)
	v_mfma_f32_32x32x16_bf16 v[66:81], v[228:231], v[102:105], v[66:81]
	s_waitcnt lgkmcnt(1)
	v_mfma_f32_32x32x16_bf16 v[82:97], v[232:235], v[98:101], v[82:97]
	s_waitcnt lgkmcnt(0)
	v_mfma_f32_32x32x16_bf16 v[66:81], v[236:239], v[98:101], v[66:81]
.Lmskip_dif_2:
	v_add_f32_e32 v182, 0, v146
	v_add_f32_e32 v182, v168, v182
	v_add_f32_e32 v182, v144, v182
	v_add_f32_e32 v182, v147, v182
	v_add_f32_e32 v182, v142, v182
	v_add_f32_e32 v182, v145, v182
	v_add_f32_e32 v182, v141, v182
	v_add_f32_e32 v182, v143, v182
	v_add_f32_e32 v182, v138, v182
	v_add_f32_e32 v182, v140, v182
	v_add_f32_e32 v182, v136, v182
	v_add_f32_e32 v182, v139, v182
	v_exp_f32_e32 v199, v184
	v_add_f32_e32 v182, v134, v182
	v_exp_f32_e32 v200, v185
	v_add_f32_e32 v182, v137, v182
	v_exp_f32_e32 v201, v186
	v_add_f32_e32 v182, v133, v182
	v_exp_f32_e32 v202, v187
	v_add_f32_e32 v182, v135, v182
	v_exp_f32_e32 v188, v188
	v_add_f32_e32 v182, v199, v182
	v_exp_f32_e32 v189, v189
	v_add_f32_e32 v182, v200, v182
	v_exp_f32_e32 v190, v190
	v_add_f32_e32 v182, v201, v182
	v_exp_f32_e32 v191, v191
	v_add_f32_e32 v182, v202, v182
	v_exp_f32_e32 v192, v192
	v_add_f32_e32 v182, v188, v182
	v_exp_f32_e32 v193, v193
	v_add_f32_e32 v182, v189, v182
	v_exp_f32_e32 v194, v194
	v_add_f32_e32 v182, v190, v182
	v_exp_f32_e32 v195, v195
	v_add_f32_e32 v182, v191, v182
	v_exp_f32_e32 v196, v196
	v_add_f32_e32 v182, v192, v182
	v_exp_f32_e32 v197, v197
	v_add_f32_e32 v182, v193, v182
	v_exp_f32_e32 v198, v198
	v_add_f32_e32 v182, v194, v182
	v_exp_f32_e32 v203, v183
	v_add_f32_e32 v182, v195, v182
	v_add_f32_e32 v182, v196, v182
	v_add_f32_e32 v182, v197, v182
	v_add_f32_e32 v182, v198, v182
	v_add_f32_e32 v182, v203, v182
	v_mov_b32_e32 v183, v182
	s_nop 1
	v_permlane32_swap_b32_e32 v182, v183
	v_cvt_pk_bf16_f32 v184, v146, v168
	v_cvt_pk_bf16_f32 v185, v144, v147
	v_cvt_pk_bf16_f32 v186, v142, v145
	v_cvt_pk_bf16_f32 v187, v141, v143
	v_cvt_pk_bf16_f32 v138, v138, v140
	v_cvt_pk_bf16_f32 v139, v136, v139
	v_cvt_pk_bf16_f32 v140, v134, v137
	v_cvt_pk_bf16_f32 v141, v133, v135
	v_cvt_pk_bf16_f32 v134, v199, v200
	v_cvt_pk_bf16_f32 v135, v201, v202
	v_cvt_pk_bf16_f32 v136, v188, v189
	v_cvt_pk_bf16_f32 v137, v190, v191
	v_cvt_pk_bf16_f32 v142, v192, v193
	v_cvt_pk_bf16_f32 v143, v194, v195
	v_cvt_pk_bf16_f32 v144, v196, v197
	v_cvt_pk_bf16_f32 v145, v198, v203
	s_nop 0
	v_permlane32_swap_b32_e32 v184, v186
	v_permlane32_swap_b32_e32 v185, v187
	v_permlane32_swap_b32_e32 v138, v140
	v_permlane32_swap_b32_e32 v139, v141
	v_permlane32_swap_b32_e32 v134, v136
	v_permlane32_swap_b32_e32 v135, v137
	v_permlane32_swap_b32_e32 v142, v144
	v_permlane32_swap_b32_e32 v143, v145
	s_waitcnt lgkmcnt(0)
	s_sub_i32 s0, s9, s25
	s_cmp_ge_i32 s0, 95
	s_cbranch_scc1 .Lmskip_dif_3
	ds_read_b64_tr_b16 v[188:189], v153 offset:0x4000
	ds_read_b64_tr_b16 v[190:191], v153 offset:0x4800
	ds_read_b64_tr_b16 v[192:193], v153 offset:0x5000
	ds_read_b64_tr_b16 v[194:195], v153 offset:0x5800
	ds_read_b64_tr_b16 v[196:197], v153 offset:0x6000
	ds_read_b64_tr_b16 v[198:199], v153 offset:0x6800
	ds_read_b64_tr_b16 v[200:201], v153 offset:0x7000
	ds_read_b64_tr_b16 v[202:203], v153 offset:0x7800
	s_nop 0
	s_waitcnt lgkmcnt(6)
	v_mfma_f32_32x32x16_bf16 v[50:65], v[184:187], v[188:191], v[50:65]
	ds_read_b64_tr_b16 v[188:189], v153 offset:0x4200
	ds_read_b64_tr_b16 v[190:191], v153 offset:0x4a00
	s_waitcnt lgkmcnt(6)
	v_mfma_f32_32x32x16_bf16 v[50:65], v[138:141], v[192:195], v[50:65]
	ds_read_b64_tr_b16 v[192:193], v153 offset:0x5200
	ds_read_b64_tr_b16 v[194:195], v153 offset:0x5a00
	s_waitcnt lgkmcnt(6)
	v_mfma_f32_32x32x16_bf16 v[50:65], v[134:137], v[196:199], v[50:65]
	ds_read_b64_tr_b16 v[196:197], v153 offset:0x6200
	ds_read_b64_tr_b16 v[198:199], v153 offset:0x6a00
	s_waitcnt lgkmcnt(6)
	v_mfma_f32_32x32x16_bf16 v[50:65], v[142:145], v[200:203], v[50:65]
	ds_read_b64_tr_b16 v[200:201], v153 offset:0x7200
	ds_read_b64_tr_b16 v[202:203], v153 offset:0x7a00
	s_waitcnt lgkmcnt(6)
	v_mfma_f32_32x32x16_bf16 v[34:49], v[184:187], v[188:191], v[34:49]
	ds_read_b64_tr_b16 v[188:189], v153 offset:0x4400
	ds_read_b64_tr_b16 v[190:191], v153 offset:0x4c00
	s_waitcnt lgkmcnt(6)
	v_mfma_f32_32x32x16_bf16 v[34:49], v[138:141], v[192:195], v[34:49]
	ds_read_b64_tr_b16 v[192:193], v153 offset:0x5400
	ds_read_b64_tr_b16 v[194:195], v153 offset:0x5c00
	s_waitcnt lgkmcnt(6)
	v_mfma_f32_32x32x16_bf16 v[34:49], v[134:137], v[196:199], v[34:49]
	ds_read_b64_tr_b16 v[196:197], v153 offset:0x6400
	ds_read_b64_tr_b16 v[198:199], v153 offset:0x6c00
	s_waitcnt lgkmcnt(6)
	v_mfma_f32_32x32x16_bf16 v[34:49], v[142:145], v[200:203], v[34:49]
	ds_read_b64_tr_b16 v[200:201], v153 offset:0x7400
	ds_read_b64_tr_b16 v[202:203], v153 offset:0x7c00
	s_waitcnt lgkmcnt(6)
	v_mfma_f32_32x32x16_bf16 v[18:33], v[184:187], v[188:191], v[18:33]
	ds_read_b64_tr_b16 v[188:189], v153 offset:0x4600
	ds_read_b64_tr_b16 v[190:191], v153 offset:0x4e00
	s_waitcnt lgkmcnt(6)
	v_mfma_f32_32x32x16_bf16 v[18:33], v[138:141], v[192:195], v[18:33]
	ds_read_b64_tr_b16 v[192:193], v153 offset:0x5600
	ds_read_b64_tr_b16 v[194:195], v153 offset:0x5e00
	s_waitcnt lgkmcnt(6)
	v_mfma_f32_32x32x16_bf16 v[18:33], v[134:137], v[196:199], v[18:33]
	ds_read_b64_tr_b16 v[196:197], v153 offset:0x6600
	ds_read_b64_tr_b16 v[198:199], v153 offset:0x6e00
	s_waitcnt lgkmcnt(6)
	v_mfma_f32_32x32x16_bf16 v[18:33], v[142:145], v[200:203], v[18:33]
	ds_read_b64_tr_b16 v[200:201], v153 offset:0x7600
	ds_read_b64_tr_b16 v[202:203], v153 offset:0x7e00
	s_waitcnt lgkmcnt(6)
	v_mfma_f32_32x32x16_bf16 v[2:17], v[184:187], v[188:191], v[2:17]
	s_waitcnt lgkmcnt(4)
	v_mfma_f32_32x32x16_bf16 v[2:17], v[138:141], v[192:195], v[2:17]
	s_waitcnt lgkmcnt(2)
	v_mfma_f32_32x32x16_bf16 v[2:17], v[134:137], v[196:199], v[2:17]
	s_waitcnt lgkmcnt(0)
	v_mfma_f32_32x32x16_bf16 v[2:17], v[142:145], v[200:203], v[2:17]
.Lmskip_dif_3:
	s_add_i32 s0, s9, 64
	s_cmp_le_i32 s0, s25
	s_cbranch_scc1 .LBB0_833
	v_cmp_gt_i32_e64 s[92:93], 26, v169
	v_cmp_gt_i32_e64 s[94:95], 27, v169
	v_cmp_gt_i32_e64 s[90:91], 25, v169
	s_and_b64 s[92:93], s[94:95], s[92:93]
	v_cmp_gt_i32_e64 s[88:89], 24, v169
	s_and_b64 s[90:91], s[92:93], s[90:91]
	v_cmp_gt_i32_e64 s[86:87], 19, v169
	s_and_b64 s[88:89], s[90:91], s[88:89]
	v_cmp_gt_i32_e64 s[84:85], 18, v169
	s_and_b64 s[86:87], s[88:89], s[86:87]
	v_cmp_gt_i32_e64 s[82:83], 17, v169
	s_and_b64 s[84:85], s[86:87], s[84:85]
	v_cmp_gt_i32_e64 s[80:81], 16, v169
	s_and_b64 s[82:83], s[84:85], s[82:83]
	v_cmp_gt_i32_e64 s[78:79], 11, v169
	s_and_b64 s[80:81], s[82:83], s[80:81]
	v_cmp_gt_i32_e64 s[76:77], 10, v169
	s_and_b64 s[78:79], s[80:81], s[78:79]
	v_cmp_gt_i32_e64 s[74:75], 9, v169
	s_and_b64 s[76:77], s[78:79], s[76:77]
	v_cmp_gt_i32_e64 s[72:73], 8, v169
	s_and_b64 s[74:75], s[76:77], s[74:75]
	v_cmp_gt_i32_e64 s[70:71], 3, v169
	s_and_b64 s[72:73], s[74:75], s[72:73]
	v_cmp_gt_i32_e64 s[68:69], 2, v169
	s_and_b64 s[70:71], s[72:73], s[70:71]
	v_cmp_gt_i32_e64 s[2:3], 1, v169
	s_and_b64 s[68:69], s[70:71], s[68:69]
	v_cmp_gt_i32_e64 s[0:1], 0, v169
	s_and_b64 s[2:3], s[68:69], s[2:3]
	s_and_b64 s[0:1], s[2:3], s[0:1]
	v_cmp_gt_i32_e64 s[66:67], 58, v169
	v_cndmask_b32_e64 v82, v82, v175, s[0:1]
	v_cmp_gt_i32_e64 s[0:1], 59, v169
	v_cmp_gt_i32_e64 s[64:65], 57, v169
	v_cmp_gt_i32_e64 s[62:63], 56, v169
	v_cndmask_b32_e64 v81, v81, v175, s[0:1]
	s_and_b64 s[0:1], s[0:1], s[66:67]
	v_cndmask_b32_e64 v80, v80, v175, s[0:1]
	s_and_b64 s[0:1], s[0:1], s[64:65]
	v_cmp_gt_i32_e64 s[60:61], 51, v169
	v_cndmask_b32_e64 v79, v79, v175, s[0:1]
	s_and_b64 s[0:1], s[0:1], s[62:63]
	v_cmp_gt_i32_e64 s[58:59], 50, v169
	v_cndmask_b32_e64 v78, v78, v175, s[0:1]
	s_and_b64 s[0:1], s[0:1], s[60:61]
	v_cmp_gt_i32_e64 s[56:57], 49, v169
	v_cndmask_b32_e64 v77, v77, v175, s[0:1]
	s_and_b64 s[0:1], s[0:1], s[58:59]
	v_cmp_gt_i32_e64 s[54:55], 48, v169
	v_cndmask_b32_e64 v76, v76, v175, s[0:1]
	s_and_b64 s[0:1], s[0:1], s[56:57]
	v_cmp_gt_i32_e64 s[52:53], 43, v169
	v_cndmask_b32_e64 v75, v75, v175, s[0:1]
	s_and_b64 s[0:1], s[0:1], s[54:55]
	v_cmp_gt_i32_e64 s[50:51], 42, v169
	v_cndmask_b32_e64 v74, v74, v175, s[0:1]
	s_and_b64 s[0:1], s[0:1], s[52:53]
	v_cmp_gt_i32_e64 s[48:49], 41, v169
	v_cndmask_b32_e64 v73, v73, v175, s[0:1]
	s_and_b64 s[0:1], s[0:1], s[50:51]
	v_cmp_gt_i32_e64 s[46:47], 40, v169
	v_cndmask_b32_e64 v72, v72, v175, s[0:1]
	s_and_b64 s[0:1], s[0:1], s[48:49]
	v_cmp_gt_i32_e64 s[44:45], 35, v169
	v_cndmask_b32_e64 v71, v71, v175, s[0:1]
	s_and_b64 s[0:1], s[0:1], s[46:47]
	v_cmp_gt_i32_e64 s[42:43], 34, v169
	v_cndmask_b32_e64 v70, v70, v175, s[0:1]
	s_and_b64 s[0:1], s[0:1], s[44:45]
	v_cmp_gt_i32_e64 s[40:41], 33, v169
	v_cndmask_b32_e64 v69, v69, v175, s[0:1]
	s_and_b64 s[0:1], s[0:1], s[42:43]
	v_cmp_gt_i32_e32 vcc, 32, v169
	v_cndmask_b32_e64 v68, v68, v175, s[0:1]
	s_and_b64 s[0:1], s[0:1], s[40:41]
	s_and_b64 vcc, s[0:1], vcc
	v_cndmask_b32_e64 v97, v97, v175, s[94:95]
	v_cndmask_b32_e64 v96, v96, v175, s[92:93]
	v_cndmask_b32_e64 v95, v95, v175, s[90:91]
	v_cndmask_b32_e64 v94, v94, v175, s[88:89]
	v_cndmask_b32_e64 v93, v93, v175, s[86:87]
	v_cndmask_b32_e64 v92, v92, v175, s[84:85]
	v_cndmask_b32_e64 v91, v91, v175, s[82:83]
	v_cndmask_b32_e64 v90, v90, v175, s[80:81]
	v_cndmask_b32_e64 v89, v89, v175, s[78:79]
	v_cndmask_b32_e64 v88, v88, v175, s[76:77]
	v_cndmask_b32_e64 v87, v87, v175, s[74:75]
	v_cndmask_b32_e64 v86, v86, v175, s[72:73]
	v_cndmask_b32_e64 v85, v85, v175, s[70:71]
	v_cndmask_b32_e64 v84, v84, v175, s[68:69]
	v_cndmask_b32_e64 v83, v83, v175, s[2:3]
	v_cndmask_b32_e64 v67, v67, v175, s[0:1]
	v_cndmask_b32_e32 v66, v66, v175, vcc

.LBB0_842:
	s_waitcnt vmcnt(0) lgkmcnt(0)
	s_lshl_b32 s9, s27, 6
	s_sub_i32 s9, s9, s25
	s_cmp_ge_i32 s9, 96
	s_cbranch_scc1 .Lmskip_dif_4
	ds_read_b128 v[66:69], v159 offset:49152
	ds_read_b128 v[70:73], v159 offset:57344
	s_waitcnt lgkmcnt(1)
	v_mfma_f32_32x32x16_bf16 v[82:97], v[66:69], v[110:113], 0
	s_waitcnt lgkmcnt(0)
	v_mfma_f32_32x32x16_bf16 v[66:81], v[70:73], v[110:113], 0
	ds_read_b128 v[110:113], v160 offset:49152
	s_waitcnt vmcnt(1)
	ds_read_b128 v[116:119], v160 offset:57344
	s_waitcnt lgkmcnt(1)
	v_mfma_f32_32x32x16_bf16 v[82:97], v[110:113], v[106:109], v[82:97]
	s_waitcnt lgkmcnt(0)
	v_mfma_f32_32x32x16_bf16 v[66:81], v[116:119], v[106:109], v[66:81]
	ds_read_b128 v[106:109], v161 offset:49152
	ds_read_b128 v[110:113], v161 offset:57344
	s_waitcnt lgkmcnt(1)
	v_mfma_f32_32x32x16_bf16 v[82:97], v[106:109], v[102:105], v[82:97]
	s_waitcnt lgkmcnt(0)
	v_mfma_f32_32x32x16_bf16 v[66:81], v[110:113], v[102:105], v[66:81]
	ds_read_b128 v[102:105], v162 offset:49152
	ds_read_b128 v[106:109], v162 offset:57344
	s_waitcnt lgkmcnt(1)
	v_mfma_f32_32x32x16_bf16 v[82:97], v[102:105], v[98:101], v[82:97]
	s_waitcnt lgkmcnt(0)
	v_mfma_f32_32x32x16_bf16 v[66:81], v[106:109], v[98:101], v[66:81]
.Lmskip_dif_4:
	v_add_f32_e32 v98, 0, v197
	v_add_f32_e32 v98, v199, v98
	v_add_f32_e32 v98, v195, v98
	v_add_f32_e32 v98, v198, v98
	v_add_f32_e32 v98, v193, v98
	v_add_f32_e32 v98, v196, v98
	v_add_f32_e32 v98, v192, v98
	v_add_f32_e32 v98, v194, v98
	v_add_f32_e32 v98, v189, v98
	v_add_f32_e32 v98, v191, v98
	v_add_f32_e32 v98, v187, v98
	v_add_f32_e32 v98, v190, v98
	v_exp_f32_e32 v108, v146
	v_add_f32_e32 v98, v185, v98
	v_exp_f32_e32 v109, v147
	v_add_f32_e32 v98, v188, v98
	v_exp_f32_e32 v110, v144
	v_add_f32_e32 v98, v184, v98
	v_exp_f32_e32 v111, v145
	v_add_f32_e32 v98, v186, v98
	v_exp_f32_e32 v112, v142
	v_add_f32_e32 v98, v108, v98
	v_exp_f32_e32 v113, v143
	v_add_f32_e32 v98, v109, v98
	v_exp_f32_e32 v115, v140
	v_add_f32_e32 v98, v110, v98
	v_exp_f32_e32 v116, v141
	v_add_f32_e32 v98, v111, v98
	v_exp_f32_e32 v117, v138
	v_add_f32_e32 v98, v112, v98
	v_exp_f32_e32 v118, v139
	v_add_f32_e32 v98, v113, v98
	v_exp_f32_e32 v119, v136
	v_add_f32_e32 v98, v115, v98
	v_exp_f32_e32 v120, v137
	v_add_f32_e32 v98, v116, v98
	v_exp_f32_e32 v121, v134
	v_add_f32_e32 v98, v117, v98
	v_exp_f32_e32 v122, v135
	v_add_f32_e32 v98, v118, v98
	v_exp_f32_e32 v123, v132
	v_add_f32_e32 v98, v119, v98
	v_exp_f32_e32 v124, v133
	v_add_f32_e32 v98, v120, v98
	v_add_f32_e32 v98, v121, v98
	v_add_f32_e32 v98, v122, v98
	v_add_f32_e32 v98, v123, v98
	v_add_f32_e32 v98, v124, v98
	v_mov_b32_e32 v99, v98
	s_nop 1
	v_permlane32_swap_b32_e32 v98, v99
	v_cvt_pk_bf16_f32 v100, v197, v199
	v_cvt_pk_bf16_f32 v101, v195, v198
	v_cvt_pk_bf16_f32 v102, v193, v196
	v_cvt_pk_bf16_f32 v103, v192, v194
	v_cvt_pk_bf16_f32 v104, v189, v191
	v_cvt_pk_bf16_f32 v105, v187, v190
	v_cvt_pk_bf16_f32 v106, v185, v188
	v_cvt_pk_bf16_f32 v107, v184, v186
	v_cvt_pk_bf16_f32 v108, v108, v109
	v_cvt_pk_bf16_f32 v109, v110, v111
	v_cvt_pk_bf16_f32 v110, v112, v113
	v_cvt_pk_bf16_f32 v111, v115, v116
	v_cvt_pk_bf16_f32 v116, v117, v118
	v_cvt_pk_bf16_f32 v117, v119, v120
	v_cvt_pk_bf16_f32 v118, v121, v122
	v_cvt_pk_bf16_f32 v119, v123, v124
	s_nop 0
	v_permlane32_swap_b32_e32 v100, v102
	v_permlane32_swap_b32_e32 v101, v103
	v_permlane32_swap_b32_e32 v104, v106
	v_permlane32_swap_b32_e32 v105, v107
	v_permlane32_swap_b32_e32 v108, v110
	v_permlane32_swap_b32_e32 v109, v111
	v_permlane32_swap_b32_e32 v116, v118
	v_permlane32_swap_b32_e32 v117, v119
	s_waitcnt vmcnt(0) lgkmcnt(0)
	s_cmp_ge_i32 s9, 160
	s_cbranch_scc1 .Lmskip_dif_5
	ds_read_b64_tr_b16 v[120:121], v153 offset:0
	ds_read_b64_tr_b16 v[122:123], v153 offset:0x800
	ds_read_b64_tr_b16 v[124:125], v153 offset:0x1000
	s_waitcnt vmcnt(0)
	ds_read_b64_tr_b16 v[126:127], v153 offset:0x1800
	ds_read_b64_tr_b16 v[128:129], v153 offset:0x2000
	ds_read_b64_tr_b16 v[130:131], v153 offset:0x2800
	ds_read_b64_tr_b16 v[132:133], v153 offset:0x3000
	ds_read_b64_tr_b16 v[134:135], v153 offset:0x3800
	s_waitcnt lgkmcnt(6)
	v_mfma_f32_32x32x16_bf16 v[50:65], v[100:103], v[120:123], v[50:65]
	ds_read_b64_tr_b16 v[120:121], v153 offset:0x200
	ds_read_b64_tr_b16 v[122:123], v153 offset:0xa00
	s_waitcnt lgkmcnt(6)
	v_mfma_f32_32x32x16_bf16 v[50:65], v[104:107], v[124:127], v[50:65]
	ds_read_b64_tr_b16 v[124:125], v153 offset:0x1200
	ds_read_b64_tr_b16 v[126:127], v153 offset:0x1a00
	s_waitcnt lgkmcnt(6)
	v_mfma_f32_32x32x16_bf16 v[50:65], v[108:111], v[128:131], v[50:65]
	ds_read_b64_tr_b16 v[128:129], v153 offset:0x2200
	ds_read_b64_tr_b16 v[130:131], v153 offset:0x2a00
	s_waitcnt lgkmcnt(6)
	v_mfma_f32_32x32x16_bf16 v[50:65], v[116:119], v[132:135], v[50:65]
	ds_read_b64_tr_b16 v[132:133], v153 offset:0x3200
	ds_read_b64_tr_b16 v[134:135], v153 offset:0x3a00
	s_waitcnt lgkmcnt(6)
	v_mfma_f32_32x32x16_bf16 v[34:49], v[100:103], v[120:123], v[34:49]
	ds_read_b64_tr_b16 v[120:121], v153 offset:0x400
	ds_read_b64_tr_b16 v[122:123], v153 offset:0xc00
	s_waitcnt lgkmcnt(6)
	v_mfma_f32_32x32x16_bf16 v[34:49], v[104:107], v[124:127], v[34:49]
	ds_read_b64_tr_b16 v[124:125], v153 offset:0x1400
	ds_read_b64_tr_b16 v[126:127], v153 offset:0x1c00
	s_waitcnt lgkmcnt(6)
	v_mfma_f32_32x32x16_bf16 v[34:49], v[108:111], v[128:131], v[34:49]
	ds_read_b64_tr_b16 v[128:129], v153 offset:0x2400
	ds_read_b64_tr_b16 v[130:131], v153 offset:0x2c00
	s_waitcnt lgkmcnt(6)
	v_mfma_f32_32x32x16_bf16 v[34:49], v[116:119], v[132:135], v[34:49]
	ds_read_b64_tr_b16 v[132:133], v153 offset:0x3400
	ds_read_b64_tr_b16 v[134:135], v153 offset:0x3c00
	s_waitcnt lgkmcnt(6)
	v_mfma_f32_32x32x16_bf16 v[18:33], v[100:103], v[120:123], v[18:33]
	ds_read_b64_tr_b16 v[120:121], v153 offset:0x600
	ds_read_b64_tr_b16 v[122:123], v153 offset:0xe00
	s_waitcnt lgkmcnt(6)
	v_mfma_f32_32x32x16_bf16 v[18:33], v[104:107], v[124:127], v[18:33]
	ds_read_b64_tr_b16 v[124:125], v153 offset:0x1600
	ds_read_b64_tr_b16 v[126:127], v153 offset:0x1e00
	s_waitcnt lgkmcnt(6)
	v_mfma_f32_32x32x16_bf16 v[18:33], v[108:111], v[128:131], v[18:33]
	ds_read_b64_tr_b16 v[128:129], v153 offset:0x2600
	ds_read_b64_tr_b16 v[130:131], v153 offset:0x2e00
	s_waitcnt lgkmcnt(6)
	v_mfma_f32_32x32x16_bf16 v[18:33], v[116:119], v[132:135], v[18:33]
	ds_read_b64_tr_b16 v[132:133], v153 offset:0x3600
	ds_read_b64_tr_b16 v[134:135], v153 offset:0x3e00
	s_waitcnt lgkmcnt(6)
	v_mfma_f32_32x32x16_bf16 v[2:17], v[100:103], v[120:123], v[2:17]
	s_waitcnt lgkmcnt(4)
	v_mfma_f32_32x32x16_bf16 v[2:17], v[104:107], v[124:127], v[2:17]
	s_waitcnt lgkmcnt(2)
	v_mfma_f32_32x32x16_bf16 v[2:17], v[108:111], v[128:131], v[2:17]
	s_waitcnt lgkmcnt(0)
	v_mfma_f32_32x32x16_bf16 v[2:17], v[116:119], v[132:135], v[2:17]
.Lmskip_dif_5:
	s_lshl_b32 s0, s27, 6
	s_add_i32 s1, s0, -1
	s_cmp_gt_i32 s1, s25
	s_cbranch_scc0 .LBB0_844
	v_subrev_u32_e32 v100, s0, v156
	v_add_u32_e32 v100, 64, v100
	v_cmp_gt_i32_e64 s[90:91], 26, v100
	v_cmp_gt_i32_e64 s[92:93], 27, v100
	v_cmp_gt_i32_e64 s[88:89], 25, v100
	s_and_b64 s[90:91], s[92:93], s[90:91]
	v_cmp_gt_i32_e64 s[86:87], 24, v100
	s_and_b64 s[88:89], s[90:91], s[88:89]
	v_cmp_gt_i32_e64 s[84:85], 19, v100
	s_and_b64 s[86:87], s[88:89], s[86:87]
	v_cmp_gt_i32_e64 s[82:83], 18, v100
	s_and_b64 s[84:85], s[86:87], s[84:85]
	v_cmp_gt_i32_e64 s[80:81], 17, v100
	s_and_b64 s[82:83], s[84:85], s[82:83]
	v_cmp_gt_i32_e64 s[78:79], 16, v100
	s_and_b64 s[80:81], s[82:83], s[80:81]
	v_cmp_gt_i32_e64 s[76:77], 11, v100
	s_and_b64 s[78:79], s[80:81], s[78:79]
	v_cmp_gt_i32_e64 s[74:75], 10, v100
	s_and_b64 s[76:77], s[78:79], s[76:77]
	v_cmp_gt_i32_e64 s[72:73], 9, v100
	s_and_b64 s[74:75], s[76:77], s[74:75]
	v_cmp_gt_i32_e64 s[70:71], 8, v100
	s_and_b64 s[72:73], s[74:75], s[72:73]
	v_cmp_gt_i32_e64 s[68:69], 3, v100
	s_and_b64 s[70:71], s[72:73], s[70:71]
	v_cmp_gt_i32_e64 s[66:67], 2, v100
	s_and_b64 s[68:69], s[70:71], s[68:69]
	v_cmp_gt_i32_e64 s[2:3], 1, v100
	s_and_b64 s[66:67], s[68:69], s[66:67]
	v_cmp_gt_i32_e64 s[0:1], 0, v100
	s_and_b64 s[2:3], s[66:67], s[2:3]
	s_and_b64 s[0:1], s[2:3], s[0:1]
	v_cmp_gt_i32_e64 s[64:65], 58, v100
	v_cndmask_b32_e64 v82, v82, v175, s[0:1]
	v_cmp_gt_i32_e64 s[0:1], 59, v100
	v_cmp_gt_i32_e64 s[62:63], 57, v100
	v_cmp_gt_i32_e64 s[60:61], 56, v100
	v_cndmask_b32_e64 v81, v81, v175, s[0:1]
	s_and_b64 s[0:1], s[0:1], s[64:65]
	v_cndmask_b32_e64 v80, v80, v175, s[0:1]
	s_and_b64 s[0:1], s[0:1], s[62:63]
	v_cmp_gt_i32_e64 s[58:59], 51, v100
	v_cndmask_b32_e64 v79, v79, v175, s[0:1]
	s_and_b64 s[0:1], s[0:1], s[60:61]
	v_cmp_gt_i32_e64 s[56:57], 50, v100
	v_cndmask_b32_e64 v78, v78, v175, s[0:1]
	s_and_b64 s[0:1], s[0:1], s[58:59]
	v_cmp_gt_i32_e64 s[54:55], 49, v100
	v_cndmask_b32_e64 v77, v77, v175, s[0:1]
	s_and_b64 s[0:1], s[0:1], s[56:57]
	v_cmp_gt_i32_e64 s[52:53], 48, v100
	v_cndmask_b32_e64 v76, v76, v175, s[0:1]
	s_and_b64 s[0:1], s[0:1], s[54:55]
	v_cmp_gt_i32_e64 s[50:51], 43, v100
	v_cndmask_b32_e64 v75, v75, v175, s[0:1]
	s_and_b64 s[0:1], s[0:1], s[52:53]
	v_cmp_gt_i32_e64 s[48:49], 42, v100
	v_cndmask_b32_e64 v74, v74, v175, s[0:1]
	s_and_b64 s[0:1], s[0:1], s[50:51]
	v_cmp_gt_i32_e64 s[46:47], 41, v100
	v_cndmask_b32_e64 v73, v73, v175, s[0:1]
	s_and_b64 s[0:1], s[0:1], s[48:49]
	v_cmp_gt_i32_e64 s[44:45], 40, v100
	v_cndmask_b32_e64 v72, v72, v175, s[0:1]
	s_and_b64 s[0:1], s[0:1], s[46:47]
	v_cmp_gt_i32_e64 s[42:43], 35, v100
	v_cndmask_b32_e64 v71, v71, v175, s[0:1]
	s_and_b64 s[0:1], s[0:1], s[44:45]
	v_cmp_gt_i32_e64 s[40:41], 34, v100
	v_cndmask_b32_e64 v70, v70, v175, s[0:1]
	s_and_b64 s[0:1], s[0:1], s[42:43]
	v_cmp_gt_i32_e64 s[38:39], 33, v100
	v_cndmask_b32_e64 v69, v69, v175, s[0:1]
	s_and_b64 s[0:1], s[0:1], s[40:41]
	v_cmp_gt_i32_e32 vcc, 32, v100
	v_cndmask_b32_e64 v68, v68, v175, s[0:1]
	s_and_b64 s[0:1], s[0:1], s[38:39]
	s_and_b64 vcc, s[0:1], vcc
	v_cndmask_b32_e64 v97, v97, v175, s[92:93]
	v_cndmask_b32_e64 v96, v96, v175, s[90:91]
	v_cndmask_b32_e64 v95, v95, v175, s[88:89]
	v_cndmask_b32_e64 v94, v94, v175, s[86:87]
	v_cndmask_b32_e64 v93, v93, v175, s[84:85]
	v_cndmask_b32_e64 v92, v92, v175, s[82:83]
	v_cndmask_b32_e64 v91, v91, v175, s[80:81]
	v_cndmask_b32_e64 v90, v90, v175, s[78:79]
	v_cndmask_b32_e64 v89, v89, v175, s[76:77]
	v_cndmask_b32_e64 v88, v88, v175, s[74:75]
	v_cndmask_b32_e64 v87, v87, v175, s[72:73]
	v_cndmask_b32_e64 v86, v86, v175, s[70:71]
	v_cndmask_b32_e64 v85, v85, v175, s[68:69]
	v_cndmask_b32_e64 v84, v84, v175, s[66:67]
	v_cndmask_b32_e64 v83, v83, v175, s[2:3]
	v_cndmask_b32_e64 v67, v67, v175, s[0:1]
	v_cndmask_b32_e32 v66, v66, v175, vcc

.LBB0_848:
	v_cndmask_b32_e64 v101, v101, v168, s[38:39]
	v_mul_f32_e32 v101, 0xbe38aa3b, v101
	v_fmamk_f32 v82, v82, 0x3e38aa3b, v101
	v_fmamk_f32 v66, v66, 0x3e38aa3b, v101
	v_fmamk_f32 v83, v83, 0x3e38aa3b, v101
	v_fmamk_f32 v67, v67, 0x3e38aa3b, v101
	v_fmamk_f32 v84, v84, 0x3e38aa3b, v101
	v_fmamk_f32 v68, v68, 0x3e38aa3b, v101
	v_fmamk_f32 v85, v85, 0x3e38aa3b, v101
	v_fmamk_f32 v69, v69, 0x3e38aa3b, v101
	v_fmamk_f32 v86, v86, 0x3e38aa3b, v101
	v_fmamk_f32 v70, v70, 0x3e38aa3b, v101
	v_fmamk_f32 v87, v87, 0x3e38aa3b, v101
	v_fmamk_f32 v71, v71, 0x3e38aa3b, v101
	v_fmamk_f32 v88, v88, 0x3e38aa3b, v101
	v_fmamk_f32 v72, v72, 0x3e38aa3b, v101
	v_fmamk_f32 v89, v89, 0x3e38aa3b, v101
	v_fmamk_f32 v73, v73, 0x3e38aa3b, v101
	v_fmamk_f32 v90, v90, 0x3e38aa3b, v101
	v_fmamk_f32 v74, v74, 0x3e38aa3b, v101
	v_fmamk_f32 v91, v91, 0x3e38aa3b, v101
	v_fmamk_f32 v75, v75, 0x3e38aa3b, v101
	v_fmamk_f32 v92, v92, 0x3e38aa3b, v101
	v_fmamk_f32 v76, v76, 0x3e38aa3b, v101
	v_fmamk_f32 v93, v93, 0x3e38aa3b, v101
	v_fmamk_f32 v77, v77, 0x3e38aa3b, v101
	v_fmamk_f32 v94, v94, 0x3e38aa3b, v101
	v_fmamk_f32 v78, v78, 0x3e38aa3b, v101
	v_fmamk_f32 v95, v95, 0x3e38aa3b, v101
	v_fmamk_f32 v79, v79, 0x3e38aa3b, v101
	v_fmamk_f32 v96, v96, 0x3e38aa3b, v101
	v_fmamk_f32 v80, v80, 0x3e38aa3b, v101
	v_fmamk_f32 v97, v97, 0x3e38aa3b, v101
	v_fmac_f32_e32 v101, 0x3e38aa3b, v81
	v_exp_f32_e32 v81, v82
	v_exp_f32_e32 v82, v83
	v_exp_f32_e32 v83, v84
	v_exp_f32_e32 v84, v85
	v_exp_f32_e32 v85, v86
	v_exp_f32_e32 v86, v87
	v_exp_f32_e32 v87, v88
	v_exp_f32_e32 v88, v89
	v_exp_f32_e32 v89, v90
	v_exp_f32_e32 v90, v91
	v_exp_f32_e32 v91, v92
	v_exp_f32_e32 v92, v93
	v_exp_f32_e32 v93, v94
	v_exp_f32_e32 v94, v95
	v_exp_f32_e32 v95, v96
	v_exp_f32_e32 v96, v97
	v_exp_f32_e32 v97, v66
	v_add_f32_e32 v66, 0, v81
	v_add_f32_e32 v66, v82, v66
	v_add_f32_e32 v66, v83, v66
	v_add_f32_e32 v66, v84, v66
	v_add_f32_e32 v66, v85, v66
	v_add_f32_e32 v66, v86, v66
	v_add_f32_e32 v66, v87, v66
	v_add_f32_e32 v66, v88, v66
	v_add_f32_e32 v66, v89, v66
	v_add_f32_e32 v66, v90, v66
	v_add_f32_e32 v66, v91, v66
	v_add_f32_e32 v66, v92, v66
	v_add_f32_e32 v66, v93, v66
	v_exp_f32_e32 v102, v67
	v_add_f32_e32 v66, v94, v66
	v_exp_f32_e32 v103, v68
	v_add_f32_e32 v66, v95, v66
	v_exp_f32_e32 v104, v69
	v_add_f32_e32 v66, v96, v66
	v_exp_f32_e32 v105, v70
	v_add_f32_e32 v66, v97, v66
	v_exp_f32_e32 v106, v71
	v_add_f32_e32 v66, v102, v66
	v_exp_f32_e32 v107, v72
	v_add_f32_e32 v66, v103, v66
	v_exp_f32_e32 v108, v73
	v_add_f32_e32 v66, v104, v66
	v_exp_f32_e32 v109, v74
	v_add_f32_e32 v66, v105, v66
	v_exp_f32_e32 v110, v75
	v_add_f32_e32 v66, v106, v66
	v_exp_f32_e32 v111, v76
	v_add_f32_e32 v66, v107, v66
	v_exp_f32_e32 v112, v77
	v_add_f32_e32 v66, v108, v66
	v_exp_f32_e32 v113, v78
	v_add_f32_e32 v66, v109, v66
	v_exp_f32_e32 v115, v79
	v_add_f32_e32 v66, v110, v66
	v_exp_f32_e32 v116, v80
	v_add_f32_e32 v66, v111, v66
	v_exp_f32_e32 v101, v101
	v_add_f32_e32 v66, v112, v66
	v_add_f32_e32 v66, v113, v66
	v_add_f32_e32 v66, v115, v66
	v_add_f32_e32 v66, v116, v66
	v_add_f32_e32 v66, v101, v66
	v_mov_b32_e32 v67, v66
	s_nop 1
	v_permlane32_swap_b32_e32 v66, v67
	v_cvt_pk_bf16_f32 v68, v81, v82
	v_cvt_pk_bf16_f32 v69, v83, v84
	v_cvt_pk_bf16_f32 v70, v85, v86
	v_cvt_pk_bf16_f32 v71, v87, v88
	v_cvt_pk_bf16_f32 v72, v89, v90
	v_cvt_pk_bf16_f32 v73, v91, v92
	v_cvt_pk_bf16_f32 v74, v93, v94
	v_cvt_pk_bf16_f32 v75, v95, v96
	v_cvt_pk_bf16_f32 v76, v97, v102
	v_cvt_pk_bf16_f32 v77, v103, v104
	v_cvt_pk_bf16_f32 v78, v105, v106
	v_cvt_pk_bf16_f32 v79, v107, v108
	v_cvt_pk_bf16_f32 v80, v109, v110
	v_cvt_pk_bf16_f32 v81, v111, v112
	v_cvt_pk_bf16_f32 v82, v113, v115
	v_cvt_pk_bf16_f32 v83, v116, v101
	s_nop 0
	v_permlane32_swap_b32_e32 v68, v70
	v_permlane32_swap_b32_e32 v69, v71
	v_permlane32_swap_b32_e32 v72, v74
	v_permlane32_swap_b32_e32 v73, v75
	v_permlane32_swap_b32_e32 v76, v78
	v_permlane32_swap_b32_e32 v77, v79
	v_permlane32_swap_b32_e32 v80, v82
	v_permlane32_swap_b32_e32 v81, v83
	s_waitcnt vmcnt(0) lgkmcnt(0)
	s_cmp_ge_i32 s9, 96
	s_cbranch_scc1 .Lmskip_dif_6
	ds_read_b64_tr_b16 v[84:85], v153 offset:0x4000
	ds_read_b64_tr_b16 v[86:87], v153 offset:0x4800
	ds_read_b64_tr_b16 v[88:89], v153 offset:0x5000
	ds_read_b64_tr_b16 v[90:91], v153 offset:0x5800
	ds_read_b64_tr_b16 v[92:93], v153 offset:0x6000
	ds_read_b64_tr_b16 v[94:95], v153 offset:0x6800
	ds_read_b64_tr_b16 v[102:103], v153 offset:0x7000
	ds_read_b64_tr_b16 v[104:105], v153 offset:0x7800
	s_nop 0
	s_waitcnt lgkmcnt(6)
	v_mfma_f32_32x32x16_bf16 v[50:65], v[68:71], v[84:87], v[50:65]
	ds_read_b64_tr_b16 v[84:85], v153 offset:0x4200
	ds_read_b64_tr_b16 v[86:87], v153 offset:0x4a00
	s_waitcnt lgkmcnt(6)
	v_mfma_f32_32x32x16_bf16 v[50:65], v[72:75], v[88:91], v[50:65]
	ds_read_b64_tr_b16 v[88:89], v153 offset:0x5200
	ds_read_b64_tr_b16 v[90:91], v153 offset:0x5a00
	s_waitcnt lgkmcnt(6)
	v_mfma_f32_32x32x16_bf16 v[50:65], v[76:79], v[92:95], v[50:65]
	ds_read_b64_tr_b16 v[92:93], v153 offset:0x6200
	ds_read_b64_tr_b16 v[94:95], v153 offset:0x6a00
	s_waitcnt lgkmcnt(6)
	v_mfma_f32_32x32x16_bf16 v[50:65], v[80:83], v[102:105], v[50:65]
	ds_read_b64_tr_b16 v[102:103], v153 offset:0x7200
	ds_read_b64_tr_b16 v[104:105], v153 offset:0x7a00
	s_waitcnt lgkmcnt(6)
	v_mfma_f32_32x32x16_bf16 v[34:49], v[68:71], v[84:87], v[34:49]
	ds_read_b64_tr_b16 v[84:85], v153 offset:0x4400
	ds_read_b64_tr_b16 v[86:87], v153 offset:0x4c00
	s_waitcnt lgkmcnt(6)
	v_mfma_f32_32x32x16_bf16 v[34:49], v[72:75], v[88:91], v[34:49]
	ds_read_b64_tr_b16 v[88:89], v153 offset:0x5400
	ds_read_b64_tr_b16 v[90:91], v153 offset:0x5c00
	s_waitcnt lgkmcnt(6)
	v_mfma_f32_32x32x16_bf16 v[34:49], v[76:79], v[92:95], v[34:49]
	ds_read_b64_tr_b16 v[92:93], v153 offset:0x6400
	ds_read_b64_tr_b16 v[94:95], v153 offset:0x6c00
	s_waitcnt lgkmcnt(6)
	v_mfma_f32_32x32x16_bf16 v[34:49], v[80:83], v[102:105], v[34:49]
	ds_read_b64_tr_b16 v[102:103], v153 offset:0x7400
	ds_read_b64_tr_b16 v[104:105], v153 offset:0x7c00
	s_waitcnt lgkmcnt(6)
	v_mfma_f32_32x32x16_bf16 v[18:33], v[68:71], v[84:87], v[18:33]
	ds_read_b64_tr_b16 v[84:85], v153 offset:0x4600
	ds_read_b64_tr_b16 v[86:87], v153 offset:0x4e00
	s_waitcnt lgkmcnt(6)
	v_mfma_f32_32x32x16_bf16 v[18:33], v[72:75], v[88:91], v[18:33]
	ds_read_b64_tr_b16 v[88:89], v153 offset:0x5600
	ds_read_b64_tr_b16 v[90:91], v153 offset:0x5e00
	s_waitcnt lgkmcnt(6)
	v_mfma_f32_32x32x16_bf16 v[18:33], v[76:79], v[92:95], v[18:33]
	ds_read_b64_tr_b16 v[92:93], v153 offset:0x6600
	ds_read_b64_tr_b16 v[94:95], v153 offset:0x6e00
	s_waitcnt lgkmcnt(6)
	v_mfma_f32_32x32x16_bf16 v[18:33], v[80:83], v[102:105], v[18:33]
	ds_read_b64_tr_b16 v[102:103], v153 offset:0x7600
	ds_read_b64_tr_b16 v[104:105], v153 offset:0x7e00
	s_waitcnt lgkmcnt(6)
	v_mfma_f32_32x32x16_bf16 v[2:17], v[68:71], v[84:87], v[2:17]
	s_waitcnt lgkmcnt(4)
	v_mfma_f32_32x32x16_bf16 v[2:17], v[72:75], v[88:91], v[2:17]
	s_waitcnt lgkmcnt(2)
	v_mfma_f32_32x32x16_bf16 v[2:17], v[76:79], v[92:95], v[2:17]
	s_waitcnt lgkmcnt(0)
	v_mfma_f32_32x32x16_bf16 v[2:17], v[80:83], v[102:105], v[2:17]
.Lmskip_dif_6:
	v_cmp_gt_u32_e32 vcc, 32, v149
	s_and_saveexec_b64 s[0:1], vcc
	v_add_f32_e32 v68, v98, v99
	v_fmac_f32_e32 v68, v157, v114
	v_add_f32_e32 v66, v66, v67
	v_fmac_f32_e32 v66, v68, v100
	ds_write_b32 v155, v66
	s_or_b64 exec, exec, s[0:1]
	s_waitcnt lgkmcnt(0)
	ds_read_b128 v[78:81], v154
	ds_read_b128 v[74:77], v154 offset:32
	ds_read_b128 v[70:73], v154 offset:64
	ds_read_b128 v[66:69], v154 offset:96
	s_lshl_b32 s0, s29, 13
	s_waitcnt lgkmcnt(3)
	v_rcp_f32_e32 v82, v78
	v_and_b32_e32 v78, 1, v150
	s_add_i32 s2, s0, 0
	v_cmp_eq_u32_e32 vcc, 0, v78
	v_lshlrev_b32_e32 v78, 10, v152
	v_lshlrev_b32_e32 v83, 1, v151
	v_mul_f32_e32 v50, v50, v82
	v_add3_u32 v78, s2, v78, v83
	s_waitcnt lgkmcnt(0)
	v_mov_b32_dpp v83, v50 quad_perm:[1,0,3,2] row_mask:0xf bank_mask:0xf bound_ctrl:1
	s_barrier
	s_and_saveexec_b64 s[0:1], vcc
	s_cbranch_execz .LBB0_852
	v_cvt_pk_bf16_f32 v50, v50, v83
	ds_write_b32 v78, v50
